# nt (non-temporal) on the read-once f32 weight streams: 6 weight-copy loops + adaLN w_ada loads
# speedup vs baseline: 1.0036x; 1.0036x over previous
; __device__ __forceinline__ void ph_adaln_partial(Frame& F) {
;     ...
;     for (int u = gw; u < 2 * NBLK * 16; u += NGW) {
;         const int layer = u / (NBLK * 16), r = u % (NBLK * 16), ks = r % 16, nb = r / 16, n0 = nb * 256 + 4 * lane;
;         const float* W = iWADA + (size_t)layer * D * NMODC + (size_t)(ks * 128) * NMODC + n0;
;         f32x4 a0 = {0.f, 0.f, 0.f, 0.f}, a1 = a0, a2 = a0, a3 = a0, a4 = a0;
; #pragma unroll 8
;         for (int kk = 0; kk < 128; ++kk) { const f32x4 w = *(const f32x4*)(W + (size_t)kk * NMODC); const int k = ks * 128 + kk;
;             a0 += w * s[k]; a1 += w * s[D + k]; a2 += w * s[2 * D + k]; a3 += w * s[3 * D + k]; a4 += w * s[4 * D + k]; }
.LBB0_27:
	v_lshl_add_u64 v[26:27], v[24:25], 0, s[0:1]
	v_add_co_u32_e32 v100, vcc, s7, v26
	global_load_dwordx4 v[28:31], v[26:27], off nt
	s_nop 0
	v_addc_co_u32_e32 v101, vcc, 0, v27, vcc
	v_add_co_u32_e32 v102, vcc, s10, v26
	v_mov_b32_e32 v68, s18
	s_nop 0
	v_addc_co_u32_e32 v103, vcc, 0, v27, vcc
	v_add_co_u32_e32 v104, vcc, s11, v26
	ds_read_b128 v[32:35], v68
	ds_read_b128 v[36:39], v68 offset:16
	ds_read_b128 v[40:43], v68 offset:8192
	ds_read_b128 v[44:47], v68 offset:8208
	ds_read_b128 v[48:51], v68 offset:16384
	ds_read_b128 v[52:55], v68 offset:16400
	ds_read_b128 v[56:59], v68 offset:24576
	ds_read_b128 v[60:63], v68 offset:24592
	ds_read_b128 v[64:67], v68 offset:32768
	ds_read_b128 v[68:71], v68 offset:32784
	v_addc_co_u32_e32 v105, vcc, 0, v27, vcc
	v_add_co_u32_e32 v106, vcc, s12, v26
	s_add_u32 s0, s0, 0x90000
	s_nop 0
	v_addc_co_u32_e32 v107, vcc, 0, v27, vcc
	v_add_co_u32_e32 v108, vcc, s13, v26
	s_addc_u32 s1, s1, 0
	s_nop 0
	v_addc_co_u32_e32 v109, vcc, 0, v27, vcc
	v_add_co_u32_e32 v110, vcc, s14, v26
	s_add_i32 s18, s18, 32
	s_nop 0
	v_addc_co_u32_e32 v111, vcc, 0, v27, vcc
	v_add_co_u32_e32 v26, vcc, s15, v26
	s_waitcnt lgkmcnt(4)
	v_mov_b32_e32 v112, v55
	v_addc_co_u32_e32 v27, vcc, 0, v27, vcc
	global_load_dwordx4 v[72:75], v[100:101], off nt
	global_load_dwordx4 v[76:79], v[102:103], off nt
	global_load_dwordx4 v[80:83], v[104:105], off nt
	global_load_dwordx4 v[84:87], v[106:107], off nt
	global_load_dwordx4 v[88:91], v[108:109], off nt
	global_load_dwordx4 v[92:95], v[110:111], off nt
	global_load_dwordx4 v[96:99], v[26:27], off nt
	v_mov_b32_e32 v26, v35
	v_mov_b32_e32 v100, v43
	v_mov_b32_e32 v102, v51
	s_waitcnt lgkmcnt(3)
	v_mov_b32_e32 v104, v59
	s_waitcnt lgkmcnt(1)
	v_mov_b32_e32 v106, v67
	v_mov_b32_e32 v108, v39
	v_mov_b32_e32 v110, v47
	v_mov_b32_e32 v114, v63
	s_waitcnt lgkmcnt(0)
	v_mov_b32_e32 v116, v71
	s_cmp_eq_u32 s0, 0x900000
	s_waitcnt vmcnt(7)
	v_pk_fma_f32 v[20:21], v[30:31], v[32:33], v[20:21] op_sel_hi:[1,0,1]
	v_pk_fma_f32 v[18:19], v[28:29], v[32:33], v[18:19] op_sel_hi:[1,0,1]
	v_pk_fma_f32 v[16:17], v[30:31], v[40:41], v[16:17] op_sel_hi:[1,0,1]
	v_pk_fma_f32 v[14:15], v[28:29], v[40:41], v[14:15] op_sel_hi:[1,0,1]
	v_pk_fma_f32 v[12:13], v[30:31], v[48:49], v[12:13] op_sel_hi:[1,0,1]
	v_pk_fma_f32 v[10:11], v[28:29], v[48:49], v[10:11] op_sel_hi:[1,0,1]
	v_pk_fma_f32 v[8:9], v[30:31], v[56:57], v[8:9] op_sel_hi:[1,0,1]
	v_pk_fma_f32 v[6:7], v[28:29], v[56:57], v[6:7] op_sel_hi:[1,0,1]
	v_pk_fma_f32 v[4:5], v[30:31], v[64:65], v[4:5] op_sel_hi:[1,0,1]
	v_pk_fma_f32 v[2:3], v[28:29], v[64:65], v[2:3] op_sel_hi:[1,0,1]
	s_waitcnt vmcnt(6)
	v_pk_fma_f32 v[18:19], v[72:73], v[32:33], v[18:19] op_sel:[0,1,0]
	v_pk_fma_f32 v[20:21], v[74:75], v[32:33], v[20:21] op_sel:[0,1,0]
	v_pk_fma_f32 v[14:15], v[72:73], v[40:41], v[14:15] op_sel:[0,1,0]
	v_pk_fma_f32 v[16:17], v[74:75], v[40:41], v[16:17] op_sel:[0,1,0]
	v_pk_fma_f32 v[10:11], v[72:73], v[48:49], v[10:11] op_sel:[0,1,0]
	v_pk_fma_f32 v[12:13], v[74:75], v[48:49], v[12:13] op_sel:[0,1,0]
	v_pk_fma_f32 v[6:7], v[72:73], v[56:57], v[6:7] op_sel:[0,1,0]
	v_pk_fma_f32 v[8:9], v[74:75], v[56:57], v[8:9] op_sel:[0,1,0]
	v_pk_fma_f32 v[2:3], v[72:73], v[64:65], v[2:3] op_sel:[0,1,0]
	v_pk_fma_f32 v[4:5], v[74:75], v[64:65], v[4:5] op_sel:[0,1,0]
	s_waitcnt vmcnt(5)
	v_pk_fma_f32 v[20:21], v[78:79], v[34:35], v[20:21] op_sel_hi:[1,0,1]
	v_pk_fma_f32 v[18:19], v[76:77], v[34:35], v[18:19] op_sel_hi:[1,0,1]
	v_pk_fma_f32 v[16:17], v[78:79], v[42:43], v[16:17] op_sel_hi:[1,0,1]
	v_pk_fma_f32 v[14:15], v[76:77], v[42:43], v[14:15] op_sel_hi:[1,0,1]
	v_pk_fma_f32 v[12:13], v[78:79], v[50:51], v[12:13] op_sel_hi:[1,0,1]
	v_pk_fma_f32 v[10:11], v[76:77], v[50:51], v[10:11] op_sel_hi:[1,0,1]
	v_pk_fma_f32 v[8:9], v[78:79], v[58:59], v[8:9] op_sel_hi:[1,0,1]
	v_pk_fma_f32 v[6:7], v[76:77], v[58:59], v[6:7] op_sel_hi:[1,0,1]
	v_pk_fma_f32 v[4:5], v[78:79], v[66:67], v[4:5] op_sel_hi:[1,0,1]
	v_pk_fma_f32 v[2:3], v[76:77], v[66:67], v[2:3] op_sel_hi:[1,0,1]
	s_waitcnt vmcnt(4)
; __device__ __forceinline__ void ph_adaln_partial(Frame& F) {
;     ...
;         for (int kk = 0; kk < 128; ++kk) { const f32x4 w = *(const f32x4*)(W + (size_t)kk * NMODC); const int k = ks * 128 + kk;
;             a0 += w * s[k]; a1 += w * s[D + k]; a2 += w * s[2 * D + k]; a3 += w * s[3 * D + k]; a4 += w * s[4 * D + k]; }
;         float* o = pMODP + ((size_t)(layer * 16 + ks) * 5) * NMODC + n0;
;         *(f32x4*)(o) = a0; *(f32x4*)(o + NMODC) = a1; *(f32x4*)(o + 2 * NMODC) = a2; *(f32x4*)(o + 3 * NMODC) = a3; *(f32x4*)(o + 4 * NMODC) = a4;
	v_pk_fma_f32 v[20:21], v[82:83], v[26:27], v[20:21] op_sel_hi:[1,0,1]
	v_pk_fma_f32 v[18:19], v[80:81], v[26:27], v[18:19] op_sel_hi:[1,0,1]
	v_pk_fma_f32 v[16:17], v[82:83], v[100:101], v[16:17] op_sel_hi:[1,0,1]
	v_pk_fma_f32 v[14:15], v[80:81], v[100:101], v[14:15] op_sel_hi:[1,0,1]
	v_pk_fma_f32 v[12:13], v[82:83], v[102:103], v[12:13] op_sel_hi:[1,0,1]
	v_pk_fma_f32 v[10:11], v[80:81], v[102:103], v[10:11] op_sel_hi:[1,0,1]
	v_pk_fma_f32 v[8:9], v[82:83], v[104:105], v[8:9] op_sel_hi:[1,0,1]
	v_pk_fma_f32 v[6:7], v[80:81], v[104:105], v[6:7] op_sel_hi:[1,0,1]
	v_pk_fma_f32 v[4:5], v[82:83], v[106:107], v[4:5] op_sel_hi:[1,0,1]
	v_pk_fma_f32 v[2:3], v[80:81], v[106:107], v[2:3] op_sel_hi:[1,0,1]
	s_waitcnt vmcnt(3)
	v_pk_fma_f32 v[20:21], v[86:87], v[36:37], v[20:21] op_sel_hi:[1,0,1]
	v_pk_fma_f32 v[18:19], v[84:85], v[36:37], v[18:19] op_sel_hi:[1,0,1]
	v_pk_fma_f32 v[16:17], v[86:87], v[44:45], v[16:17] op_sel_hi:[1,0,1]
	v_pk_fma_f32 v[14:15], v[84:85], v[44:45], v[14:15] op_sel_hi:[1,0,1]
	v_pk_fma_f32 v[12:13], v[86:87], v[52:53], v[12:13] op_sel_hi:[1,0,1]
	v_pk_fma_f32 v[10:11], v[84:85], v[52:53], v[10:11] op_sel_hi:[1,0,1]
	v_pk_fma_f32 v[8:9], v[86:87], v[60:61], v[8:9] op_sel_hi:[1,0,1]
	v_pk_fma_f32 v[6:7], v[84:85], v[60:61], v[6:7] op_sel_hi:[1,0,1]
	v_pk_fma_f32 v[4:5], v[86:87], v[68:69], v[4:5] op_sel_hi:[1,0,1]
	v_pk_fma_f32 v[2:3], v[84:85], v[68:69], v[2:3] op_sel_hi:[1,0,1]
	s_waitcnt vmcnt(2)
	v_pk_fma_f32 v[20:21], v[90:91], v[36:37], v[20:21] op_sel:[0,1,0]
	v_pk_fma_f32 v[18:19], v[88:89], v[36:37], v[18:19] op_sel:[0,1,0]
	v_pk_fma_f32 v[16:17], v[90:91], v[44:45], v[16:17] op_sel:[0,1,0]
	v_pk_fma_f32 v[14:15], v[88:89], v[44:45], v[14:15] op_sel:[0,1,0]
	v_pk_fma_f32 v[12:13], v[90:91], v[52:53], v[12:13] op_sel:[0,1,0]
	v_pk_fma_f32 v[10:11], v[88:89], v[52:53], v[10:11] op_sel:[0,1,0]
	v_pk_fma_f32 v[8:9], v[90:91], v[60:61], v[8:9] op_sel:[0,1,0]
	v_pk_fma_f32 v[6:7], v[88:89], v[60:61], v[6:7] op_sel:[0,1,0]
	v_pk_fma_f32 v[4:5], v[90:91], v[68:69], v[4:5] op_sel:[0,1,0]
	v_pk_fma_f32 v[2:3], v[88:89], v[68:69], v[2:3] op_sel:[0,1,0]
	s_waitcnt vmcnt(1)
	v_pk_fma_f32 v[20:21], v[94:95], v[38:39], v[20:21] op_sel_hi:[1,0,1]
	v_pk_fma_f32 v[18:19], v[92:93], v[38:39], v[18:19] op_sel_hi:[1,0,1]
	v_pk_fma_f32 v[16:17], v[94:95], v[46:47], v[16:17] op_sel_hi:[1,0,1]
	v_pk_fma_f32 v[14:15], v[92:93], v[46:47], v[14:15] op_sel_hi:[1,0,1]
	v_pk_fma_f32 v[12:13], v[94:95], v[54:55], v[12:13] op_sel_hi:[1,0,1]
	v_pk_fma_f32 v[10:11], v[92:93], v[54:55], v[10:11] op_sel_hi:[1,0,1]
	v_pk_fma_f32 v[8:9], v[94:95], v[62:63], v[8:9] op_sel_hi:[1,0,1]
	v_pk_fma_f32 v[6:7], v[92:93], v[62:63], v[6:7] op_sel_hi:[1,0,1]
	v_pk_fma_f32 v[4:5], v[94:95], v[70:71], v[4:5] op_sel_hi:[1,0,1]
	v_pk_fma_f32 v[2:3], v[92:93], v[70:71], v[2:3] op_sel_hi:[1,0,1]
	s_waitcnt vmcnt(0)
	v_pk_fma_f32 v[20:21], v[98:99], v[108:109], v[20:21] op_sel_hi:[1,0,1]
	v_pk_fma_f32 v[18:19], v[96:97], v[108:109], v[18:19] op_sel_hi:[1,0,1]
	v_pk_fma_f32 v[16:17], v[98:99], v[110:111], v[16:17] op_sel_hi:[1,0,1]
	v_pk_fma_f32 v[14:15], v[96:97], v[110:111], v[14:15] op_sel_hi:[1,0,1]
	v_pk_fma_f32 v[12:13], v[98:99], v[112:113], v[12:13] op_sel_hi:[1,0,1]
	v_pk_fma_f32 v[10:11], v[96:97], v[112:113], v[10:11] op_sel_hi:[1,0,1]
	v_pk_fma_f32 v[8:9], v[98:99], v[114:115], v[8:9] op_sel_hi:[1,0,1]
	v_pk_fma_f32 v[6:7], v[96:97], v[114:115], v[6:7] op_sel_hi:[1,0,1]
	v_pk_fma_f32 v[4:5], v[98:99], v[116:117], v[4:5] op_sel_hi:[1,0,1]
	v_pk_fma_f32 v[2:3], v[96:97], v[116:117], v[2:3] op_sel_hi:[1,0,1]
	s_cbranch_scc0 .LBB0_27
	s_lshl_b32 s0, s16, 4
	s_add_i32 s0, s0, s17
	s_mul_i32 s1, s0, 5
	s_mul_i32 s0, s0, 0x5a000
	s_mul_hi_i32 s1, s1, 0x12000
	s_add_u32 s0, s5, s0
	s_addc_u32 s1, s6, s1
	v_lshl_add_u64 v[22:23], v[22:23], 2, s[0:1]
	global_store_dwordx4 v[22:23], v[18:21], off
	s_add_i32 s4, s4, s33
	s_cmpk_gt_i32 s4, 0x8ff
	v_add_co_u32_e32 v18, vcc, s7, v22
	s_nop 1
	v_addc_co_u32_e32 v19, vcc, 0, v23, vcc
	global_store_dwordx4 v[18:19], v[14:17], off
	s_nop 1
	v_add_co_u32_e32 v14, vcc, 0x24000, v22
	s_nop 1
	v_addc_co_u32_e32 v15, vcc, 0, v23, vcc
	global_store_dwordx4 v[14:15], v[10:13], off
	s_nop 1
	v_add_co_u32_e32 v10, vcc, 0x36000, v22
	s_nop 1
	v_addc_co_u32_e32 v11, vcc, 0, v23, vcc
	global_store_dwordx4 v[10:11], v[6:9], off
	s_nop 1
	v_add_co_u32_e32 v6, vcc, 0x48000, v22
	s_nop 1
	v_addc_co_u32_e32 v7, vcc, 0, v23, vcc
	global_store_dwordx4 v[6:7], v[2:5], off
	s_cbranch_scc0 .LBB0_26

; __device__ __forceinline__ void tr_load(const TrItem& t, f32x4 (&v)[16], int lane) {
;     const int c4 = 4 * (lane & 15), kq = lane >> 4; const bool okc = t.n0 + c4 < t.N;
; #pragma unroll
;     for (int i = 0; i < 16; ++i) { v[i] = (f32x4){0.f, 0.f, 0.f, 0.f}; if (okc) v[i] = *(const f32x4*)(t.W + (size_t)(t.k0 + 4 * i + kq) * t.N + t.n0 + c4); }
; }
.LBB0_38:
	v_lshlrev_b32_e32 v1, 2, v68
	v_and_b32_e32 v6, 60, v1
	v_add_u32_e32 v2, s18, v6
	v_cmp_gt_i32_e32 vcc, s37, v2
	v_mov_b32_e32 v2, 0
	v_mov_b32_e32 v4, v2
	v_mov_b32_e32 v5, v2
	v_lshrrev_b32_e32 v1, 4, v68
	v_mov_b32_e32 v3, v2
	v_lshlrev_b32_e32 v66, 2, v6
	v_mov_b64_e32 v[12:13], v[4:5]
	v_mov_b64_e32 v[8:9], v[4:5]
	v_add_u32_e32 v1, s14, v1
	v_mov_b64_e32 v[10:11], v[2:3]
	v_mov_b64_e32 v[6:7], v[2:3]
	s_and_saveexec_b64 s[24:25], vcc
	s_cbranch_execz .LBB0_40
	v_mad_u64_u32 v[6:7], s[26:27], s37, v1, 0
	v_ashrrev_i32_e32 v9, 31, v1
	v_mov_b32_e32 v8, v7
	v_mad_u64_u32 v[8:9], s[26:27], s37, v9, v[8:9]
	v_mov_b32_e32 v7, v8
	s_ashr_i32 s19, s18, 31
	v_lshl_add_u64 v[6:7], v[6:7], 2, s[22:23]
	s_lshl_b64 s[26:27], s[18:19], 2
	v_lshl_add_u64 v[6:7], v[6:7], 0, s[26:27]
	v_mov_b32_e32 v67, v2
	v_lshl_add_u64 v[14:15], v[6:7], 0, v[66:67]
	v_add_u32_e32 v6, 4, v1
	v_ashrrev_i32_e32 v9, 31, v6
	v_mad_u64_u32 v[6:7], s[28:29], s37, v6, 0
	v_mov_b32_e32 v8, v7
	v_mad_u64_u32 v[8:9], s[28:29], s37, v9, v[8:9]
	v_mov_b32_e32 v7, v8
	v_lshl_add_u64 v[6:7], v[6:7], 2, s[22:23]
	v_lshl_add_u64 v[6:7], v[6:7], 0, s[26:27]
	v_lshl_add_u64 v[16:17], v[6:7], 0, v[66:67]
	global_load_dwordx4 v[6:9], v[14:15], off nt
	global_load_dwordx4 v[10:13], v[16:17], off nt
.LBB0_40:
	s_or_b64 exec, exec, s[24:25]
	v_mov_b64_e32 v[16:17], v[4:5]
	v_mov_b64_e32 v[14:15], v[2:3]
	s_and_saveexec_b64 s[24:25], vcc
	s_cbranch_execz .LBB0_42
	v_add_u32_e32 v2, 8, v1
	v_ashrrev_i32_e32 v5, 31, v2
	v_mad_u64_u32 v[2:3], s[26:27], s37, v2, 0
	v_mov_b32_e32 v4, v3
	v_mad_u64_u32 v[4:5], s[26:27], s37, v5, v[4:5]
	v_mov_b32_e32 v3, v4
	s_ashr_i32 s19, s18, 31
	v_lshl_add_u64 v[2:3], v[2:3], 2, s[22:23]
	s_lshl_b64 s[26:27], s[18:19], 2
	v_lshl_add_u64 v[2:3], v[2:3], 0, s[26:27]
	v_mov_b32_e32 v67, 0
	v_lshl_add_u64 v[18:19], v[2:3], 0, v[66:67]
	v_add_u32_e32 v2, 12, v1
	v_ashrrev_i32_e32 v5, 31, v2
	v_mad_u64_u32 v[2:3], s[28:29], s37, v2, 0
	v_mov_b32_e32 v4, v3
	v_mad_u64_u32 v[4:5], s[28:29], s37, v5, v[4:5]
	v_mov_b32_e32 v3, v4
	v_lshl_add_u64 v[2:3], v[2:3], 2, s[22:23]
	v_lshl_add_u64 v[2:3], v[2:3], 0, s[26:27]
	v_lshl_add_u64 v[20:21], v[2:3], 0, v[66:67]
	global_load_dwordx4 v[14:17], v[18:19], off nt
	global_load_dwordx4 v[2:5], v[20:21], off nt
.LBB0_42:
	s_or_b64 exec, exec, s[24:25]
	v_mov_b32_e32 v18, 0
	v_mov_b32_e32 v20, v18
	v_mov_b32_e32 v21, v18
	v_mov_b32_e32 v19, v18
	v_mov_b64_e32 v[28:29], v[20:21]
	v_mov_b64_e32 v[24:25], v[20:21]
	v_mov_b64_e32 v[26:27], v[18:19]
	v_mov_b64_e32 v[22:23], v[18:19]
	s_and_saveexec_b64 s[24:25], vcc
	s_cbranch_execz .LBB0_44
	v_add_u32_e32 v22, 16, v1
	v_ashrrev_i32_e32 v25, 31, v22
	v_mad_u64_u32 v[22:23], s[26:27], s37, v22, 0
	v_mov_b32_e32 v24, v23
	v_mad_u64_u32 v[24:25], s[26:27], s37, v25, v[24:25]
	v_mov_b32_e32 v23, v24
	s_ashr_i32 s19, s18, 31
	v_lshl_add_u64 v[22:23], v[22:23], 2, s[22:23]
	s_lshl_b64 s[26:27], s[18:19], 2
	v_lshl_add_u64 v[22:23], v[22:23], 0, s[26:27]
	v_mov_b32_e32 v67, v18
	v_lshl_add_u64 v[30:31], v[22:23], 0, v[66:67]
	v_add_u32_e32 v22, 20, v1
	v_ashrrev_i32_e32 v25, 31, v22
	v_mad_u64_u32 v[22:23], s[28:29], s37, v22, 0
	v_mov_b32_e32 v24, v23
	v_mad_u64_u32 v[24:25], s[28:29], s37, v25, v[24:25]
	v_mov_b32_e32 v23, v24
	v_lshl_add_u64 v[22:23], v[22:23], 2, s[22:23]
	v_lshl_add_u64 v[22:23], v[22:23], 0, s[26:27]
	v_lshl_add_u64 v[32:33], v[22:23], 0, v[66:67]
	global_load_dwordx4 v[22:25], v[30:31], off nt
	global_load_dwordx4 v[26:29], v[32:33], off nt
.LBB0_44:
	s_or_b64 exec, exec, s[24:25]
	v_mov_b64_e32 v[32:33], v[20:21]
	v_mov_b64_e32 v[30:31], v[18:19]
	s_and_saveexec_b64 s[24:25], vcc
	s_cbranch_execz .LBB0_46
	v_add_u32_e32 v18, 24, v1
	v_ashrrev_i32_e32 v21, 31, v18
	v_mad_u64_u32 v[18:19], s[26:27], s37, v18, 0
	v_mov_b32_e32 v20, v19
	v_mad_u64_u32 v[20:21], s[26:27], s37, v21, v[20:21]
	v_mov_b32_e32 v19, v20
	s_ashr_i32 s19, s18, 31
	v_lshl_add_u64 v[18:19], v[18:19], 2, s[22:23]
	s_lshl_b64 s[26:27], s[18:19], 2
	v_lshl_add_u64 v[18:19], v[18:19], 0, s[26:27]
	v_mov_b32_e32 v67, 0
	v_lshl_add_u64 v[34:35], v[18:19], 0, v[66:67]
	v_add_u32_e32 v18, 28, v1
	v_ashrrev_i32_e32 v21, 31, v18
	v_mad_u64_u32 v[18:19], s[28:29], s37, v18, 0
	v_mov_b32_e32 v20, v19
	v_mad_u64_u32 v[20:21], s[28:29], s37, v21, v[20:21]
	v_mov_b32_e32 v19, v20
	v_lshl_add_u64 v[18:19], v[18:19], 2, s[22:23]
	v_lshl_add_u64 v[18:19], v[18:19], 0, s[26:27]
	v_lshl_add_u64 v[36:37], v[18:19], 0, v[66:67]
	global_load_dwordx4 v[30:33], v[34:35], off nt
	global_load_dwordx4 v[18:21], v[36:37], off nt
; __device__ __forceinline__ void tr_load(const TrItem& t, f32x4 (&v)[16], int lane) {
;     const int c4 = 4 * (lane & 15), kq = lane >> 4; const bool okc = t.n0 + c4 < t.N;
; #pragma unroll
;     for (int i = 0; i < 16; ++i) { v[i] = (f32x4){0.f, 0.f, 0.f, 0.f}; if (okc) v[i] = *(const f32x4*)(t.W + (size_t)(t.k0 + 4 * i + kq) * t.N + t.n0 + c4); }
; }
.LBB0_46:
	s_or_b64 exec, exec, s[24:25]
	v_mov_b32_e32 v34, 0
	v_mov_b32_e32 v36, v34
	v_mov_b32_e32 v37, v34
	v_mov_b32_e32 v35, v34
	v_mov_b64_e32 v[44:45], v[36:37]
	v_mov_b64_e32 v[40:41], v[36:37]
	v_mov_b64_e32 v[42:43], v[34:35]
	v_mov_b64_e32 v[38:39], v[34:35]
	s_and_saveexec_b64 s[24:25], vcc
	s_cbranch_execz .LBB0_48
	v_add_u32_e32 v38, 32, v1
	v_ashrrev_i32_e32 v41, 31, v38
	v_mad_u64_u32 v[38:39], s[26:27], s37, v38, 0
	v_mov_b32_e32 v40, v39
	v_mad_u64_u32 v[40:41], s[26:27], s37, v41, v[40:41]
	v_mov_b32_e32 v39, v40
	s_ashr_i32 s19, s18, 31
	v_lshl_add_u64 v[38:39], v[38:39], 2, s[22:23]
	s_lshl_b64 s[26:27], s[18:19], 2
	v_lshl_add_u64 v[38:39], v[38:39], 0, s[26:27]
	v_mov_b32_e32 v67, v34
	v_lshl_add_u64 v[46:47], v[38:39], 0, v[66:67]
	v_add_u32_e32 v38, 36, v1
	v_ashrrev_i32_e32 v41, 31, v38
	v_mad_u64_u32 v[38:39], s[28:29], s37, v38, 0
	v_mov_b32_e32 v40, v39
	v_mad_u64_u32 v[40:41], s[28:29], s37, v41, v[40:41]
	v_mov_b32_e32 v39, v40
	v_lshl_add_u64 v[38:39], v[38:39], 2, s[22:23]
	v_lshl_add_u64 v[38:39], v[38:39], 0, s[26:27]
	v_lshl_add_u64 v[48:49], v[38:39], 0, v[66:67]
	global_load_dwordx4 v[38:41], v[46:47], off nt
	global_load_dwordx4 v[42:45], v[48:49], off nt
.LBB0_48:
	s_or_b64 exec, exec, s[24:25]
	v_mov_b64_e32 v[48:49], v[36:37]
	v_mov_b64_e32 v[46:47], v[34:35]
	s_and_saveexec_b64 s[24:25], vcc
	s_cbranch_execz .LBB0_50
	v_add_u32_e32 v34, 40, v1
	v_ashrrev_i32_e32 v37, 31, v34
	v_mad_u64_u32 v[34:35], s[26:27], s37, v34, 0
	v_mov_b32_e32 v36, v35
	v_mad_u64_u32 v[36:37], s[26:27], s37, v37, v[36:37]
	v_mov_b32_e32 v35, v36
	s_ashr_i32 s19, s18, 31
	v_lshl_add_u64 v[34:35], v[34:35], 2, s[22:23]
	s_lshl_b64 s[26:27], s[18:19], 2
	v_lshl_add_u64 v[34:35], v[34:35], 0, s[26:27]
	v_mov_b32_e32 v67, 0
	v_lshl_add_u64 v[50:51], v[34:35], 0, v[66:67]
	v_add_u32_e32 v34, 44, v1
	v_ashrrev_i32_e32 v37, 31, v34
	v_mad_u64_u32 v[34:35], s[28:29], s37, v34, 0
	v_mov_b32_e32 v36, v35
	v_mad_u64_u32 v[36:37], s[28:29], s37, v37, v[36:37]
	v_mov_b32_e32 v35, v36
	v_lshl_add_u64 v[34:35], v[34:35], 2, s[22:23]
	v_lshl_add_u64 v[34:35], v[34:35], 0, s[26:27]
	v_lshl_add_u64 v[52:53], v[34:35], 0, v[66:67]
	global_load_dwordx4 v[46:49], v[50:51], off nt
	global_load_dwordx4 v[34:37], v[52:53], off nt
.LBB0_50:
	s_or_b64 exec, exec, s[24:25]
	v_mov_b32_e32 v50, 0
	v_mov_b32_e32 v52, v50
	v_mov_b32_e32 v53, v50
	v_mov_b32_e32 v51, v50
	v_mov_b64_e32 v[60:61], v[52:53]
	v_mov_b64_e32 v[56:57], v[52:53]
	v_mov_b64_e32 v[58:59], v[50:51]
	v_mov_b64_e32 v[54:55], v[50:51]
	s_and_saveexec_b64 s[24:25], vcc
	s_cbranch_execz .LBB0_52
	v_add_u32_e32 v54, 48, v1
	v_ashrrev_i32_e32 v57, 31, v54
	v_mad_u64_u32 v[54:55], s[26:27], s37, v54, 0
	v_mov_b32_e32 v56, v55
	v_mad_u64_u32 v[56:57], s[26:27], s37, v57, v[56:57]
	v_mov_b32_e32 v55, v56
	s_ashr_i32 s19, s18, 31
	v_lshl_add_u64 v[54:55], v[54:55], 2, s[22:23]
	s_lshl_b64 s[26:27], s[18:19], 2
	v_lshl_add_u64 v[54:55], v[54:55], 0, s[26:27]
	v_mov_b32_e32 v67, v50
	v_lshl_add_u64 v[62:63], v[54:55], 0, v[66:67]
	v_add_u32_e32 v54, 52, v1
	v_ashrrev_i32_e32 v57, 31, v54
	v_mad_u64_u32 v[54:55], s[28:29], s37, v54, 0
	v_mov_b32_e32 v56, v55
	v_mad_u64_u32 v[56:57], s[28:29], s37, v57, v[56:57]
	v_mov_b32_e32 v55, v56
	v_lshl_add_u64 v[54:55], v[54:55], 2, s[22:23]
	v_lshl_add_u64 v[54:55], v[54:55], 0, s[26:27]
	v_lshl_add_u64 v[64:65], v[54:55], 0, v[66:67]
	global_load_dwordx4 v[54:57], v[62:63], off nt
	global_load_dwordx4 v[58:61], v[64:65], off nt
.LBB0_52:
	s_or_b64 exec, exec, s[24:25]
	v_mov_b64_e32 v[64:65], v[52:53]
	v_mov_b64_e32 v[62:63], v[50:51]
	s_and_saveexec_b64 s[24:25], vcc
	s_cbranch_execz .LBB0_54
	v_add_u32_e32 v50, 56, v1
	v_ashrrev_i32_e32 v53, 31, v50
	v_mad_u64_u32 v[50:51], s[26:27], s37, v50, 0
	v_mov_b32_e32 v52, v51
	v_mad_u64_u32 v[52:53], s[26:27], s37, v53, v[52:53]
	v_mov_b32_e32 v51, v52
	s_ashr_i32 s19, s18, 31
	v_lshl_add_u64 v[50:51], v[50:51], 2, s[22:23]
	s_lshl_b64 s[26:27], s[18:19], 2
	v_lshl_add_u64 v[50:51], v[50:51], 0, s[26:27]
	v_mov_b32_e32 v67, 0
	v_add_u32_e32 v1, 60, v1
	v_lshl_add_u64 v[70:71], v[50:51], 0, v[66:67]
	v_mad_u64_u32 v[50:51], s[28:29], s37, v1, 0
	v_ashrrev_i32_e32 v53, 31, v1
	v_mov_b32_e32 v52, v51
	v_mad_u64_u32 v[52:53], s[28:29], s37, v53, v[52:53]
	v_mov_b32_e32 v51, v52
	v_lshl_add_u64 v[50:51], v[50:51], 2, s[22:23]
	v_lshl_add_u64 v[50:51], v[50:51], 0, s[26:27]
	v_lshl_add_u64 v[66:67], v[50:51], 0, v[66:67]
	global_load_dwordx4 v[50:53], v[70:71], off nt
	global_load_dwordx4 v[62:65], v[66:67], off nt

; __device__ __forceinline__ void tr_load(const TrItem& t, f32x4 (&v)[16], int lane) {
;     const int c4 = 4 * (lane & 15), kq = lane >> 4; const bool okc = t.n0 + c4 < t.N;
; #pragma unroll
;     for (int i = 0; i < 16; ++i) { v[i] = (f32x4){0.f, 0.f, 0.f, 0.f}; if (okc) v[i] = *(const f32x4*)(t.W + (size_t)(t.k0 + 4 * i + kq) * t.N + t.n0 + c4); }
; }
;     ...
;     for (; it < it1; it += NGW) {
;         const bool more = it + NGW < it1;
;         if (more) { TR_DESCRIBE(it + NGW, tn); tr_load(tn, vn, lane); }
.LBB0_64:
	v_or_b32_e32 v67, s20, v138
	v_mov_b32_e32 v68, v66
	v_mov_b32_e32 v69, v66
	v_cmp_gt_i32_e32 vcc, s43, v67
	v_mov_b32_e32 v67, v66
	v_mov_b64_e32 v[72:73], v[68:69]
	v_mov_b64_e32 v[76:77], v[68:69]
	v_lshlrev_b32_e32 v134, 2, v138
	v_mov_b64_e32 v[70:71], v[66:67]
	v_mov_b64_e32 v[74:75], v[66:67]
	s_and_saveexec_b64 s[30:31], vcc
	s_cbranch_execz .LBB0_66
	v_add_u32_e32 v70, s41, v1
	v_ashrrev_i32_e32 v73, 31, v70
	v_mad_u64_u32 v[70:71], s[46:47], s43, v70, 0
	v_mov_b32_e32 v72, v71
	v_mad_u64_u32 v[72:73], s[46:47], s43, v73, v[72:73]
	v_mov_b32_e32 v71, v72
	v_add_u32_e32 v72, s41, v139
	v_ashrrev_i32_e32 v75, 31, v72
	v_mad_u64_u32 v[72:73], s[48:49], s43, v72, 0
	v_mov_b32_e32 v74, v73
	v_mad_u64_u32 v[74:75], s[48:49], s43, v75, v[74:75]
	s_ashr_i32 s21, s20, 31
	v_mov_b32_e32 v73, v74
	v_lshl_add_u64 v[70:71], v[70:71], 2, s[28:29]
	s_lshl_b64 s[46:47], s[20:21], 2
	v_lshl_add_u64 v[72:73], v[72:73], 2, s[28:29]
	v_lshl_add_u64 v[70:71], v[70:71], 0, s[46:47]
	v_mov_b32_e32 v135, v66
	v_lshl_add_u64 v[72:73], v[72:73], 0, s[46:47]
	v_lshl_add_u64 v[70:71], v[70:71], 0, v[134:135]
	v_lshl_add_u64 v[72:73], v[72:73], 0, v[134:135]
	global_load_dwordx4 v[74:77], v[70:71], off nt
	s_nop 0
	global_load_dwordx4 v[70:73], v[72:73], off nt
.LBB0_66:
	s_or_b64 exec, exec, s[30:31]
	v_mov_b64_e32 v[80:81], v[68:69]
	v_mov_b64_e32 v[84:85], v[68:69]
	v_mov_b64_e32 v[78:79], v[66:67]
	v_mov_b64_e32 v[82:83], v[66:67]
	s_and_saveexec_b64 s[30:31], vcc
	s_cbranch_execz .LBB0_68
	v_add_u32_e32 v67, s41, v141
	v_mad_u64_u32 v[68:69], s[46:47], s43, v67, 0
	v_ashrrev_i32_e32 v79, 31, v67
	v_mov_b32_e32 v78, v69
	v_mad_u64_u32 v[78:79], s[46:47], s43, v79, v[78:79]
	v_add_u32_e32 v67, s41, v142
	v_mov_b32_e32 v69, v78
	v_mad_u64_u32 v[78:79], s[48:49], s43, v67, 0
	v_ashrrev_i32_e32 v81, 31, v67
	v_mov_b32_e32 v80, v79
	v_mad_u64_u32 v[80:81], s[48:49], s43, v81, v[80:81]
	s_ashr_i32 s21, s20, 31
	v_mov_b32_e32 v79, v80
	v_lshl_add_u64 v[68:69], v[68:69], 2, s[28:29]
	s_lshl_b64 s[46:47], s[20:21], 2
	v_lshl_add_u64 v[78:79], v[78:79], 2, s[28:29]
	v_lshl_add_u64 v[68:69], v[68:69], 0, s[46:47]
	v_mov_b32_e32 v135, v66
	v_lshl_add_u64 v[78:79], v[78:79], 0, s[46:47]
	v_lshl_add_u64 v[68:69], v[68:69], 0, v[134:135]
	v_lshl_add_u64 v[78:79], v[78:79], 0, v[134:135]
	global_load_dwordx4 v[82:85], v[68:69], off nt
	s_nop 0
	global_load_dwordx4 v[78:81], v[78:79], off nt
.LBB0_68:
	s_or_b64 exec, exec, s[30:31]
	v_mov_b32_e32 v68, v66
	v_mov_b32_e32 v69, v66
	v_mov_b32_e32 v67, v66
	v_mov_b64_e32 v[88:89], v[68:69]
	v_mov_b64_e32 v[92:93], v[68:69]
	v_mov_b64_e32 v[86:87], v[66:67]
	v_mov_b64_e32 v[90:91], v[66:67]
	s_and_saveexec_b64 s[30:31], vcc
	s_cbranch_execz .LBB0_70
	v_add_u32_e32 v86, s41, v143
	v_ashrrev_i32_e32 v89, 31, v86
	v_mad_u64_u32 v[86:87], s[46:47], s43, v86, 0
	v_mov_b32_e32 v88, v87
	v_mad_u64_u32 v[88:89], s[46:47], s43, v89, v[88:89]
	v_mov_b32_e32 v87, v88
	v_add_u32_e32 v88, s41, v144
	v_ashrrev_i32_e32 v91, 31, v88
	v_mad_u64_u32 v[88:89], s[48:49], s43, v88, 0
	v_mov_b32_e32 v90, v89
	v_mad_u64_u32 v[90:91], s[48:49], s43, v91, v[90:91]
	s_ashr_i32 s21, s20, 31
	v_mov_b32_e32 v89, v90
	v_lshl_add_u64 v[86:87], v[86:87], 2, s[28:29]
	s_lshl_b64 s[46:47], s[20:21], 2
	v_lshl_add_u64 v[88:89], v[88:89], 2, s[28:29]
	v_lshl_add_u64 v[86:87], v[86:87], 0, s[46:47]
	v_mov_b32_e32 v135, v66
	v_lshl_add_u64 v[88:89], v[88:89], 0, s[46:47]
	v_lshl_add_u64 v[86:87], v[86:87], 0, v[134:135]
	v_lshl_add_u64 v[88:89], v[88:89], 0, v[134:135]
	global_load_dwordx4 v[90:93], v[86:87], off nt
	s_nop 0
	global_load_dwordx4 v[86:89], v[88:89], off nt
.LBB0_70:
	s_or_b64 exec, exec, s[30:31]
	v_mov_b64_e32 v[96:97], v[68:69]
	v_mov_b64_e32 v[100:101], v[68:69]
	v_mov_b64_e32 v[94:95], v[66:67]
	v_mov_b64_e32 v[98:99], v[66:67]
	s_and_saveexec_b64 s[30:31], vcc
	s_cbranch_execz .LBB0_72
	v_add_u32_e32 v67, s41, v145
	v_mad_u64_u32 v[68:69], s[46:47], s43, v67, 0
	v_ashrrev_i32_e32 v95, 31, v67
	v_mov_b32_e32 v94, v69
	v_mad_u64_u32 v[94:95], s[46:47], s43, v95, v[94:95]
	v_add_u32_e32 v67, s41, v146
	v_mov_b32_e32 v69, v94
	v_mad_u64_u32 v[94:95], s[48:49], s43, v67, 0
	v_ashrrev_i32_e32 v97, 31, v67
	v_mov_b32_e32 v96, v95
	v_mad_u64_u32 v[96:97], s[48:49], s43, v97, v[96:97]
	s_ashr_i32 s21, s20, 31
	v_mov_b32_e32 v95, v96
	v_lshl_add_u64 v[68:69], v[68:69], 2, s[28:29]
	s_lshl_b64 s[46:47], s[20:21], 2
	v_lshl_add_u64 v[94:95], v[94:95], 2, s[28:29]
	v_lshl_add_u64 v[68:69], v[68:69], 0, s[46:47]
	v_mov_b32_e32 v135, v66
	v_lshl_add_u64 v[94:95], v[94:95], 0, s[46:47]
	v_lshl_add_u64 v[68:69], v[68:69], 0, v[134:135]
	v_lshl_add_u64 v[94:95], v[94:95], 0, v[134:135]
	global_load_dwordx4 v[98:101], v[68:69], off nt
	s_nop 0
	global_load_dwordx4 v[94:97], v[94:95], off nt
; __device__ __forceinline__ void tr_load(const TrItem& t, f32x4 (&v)[16], int lane) {
;     const int c4 = 4 * (lane & 15), kq = lane >> 4; const bool okc = t.n0 + c4 < t.N;
; #pragma unroll
;     for (int i = 0; i < 16; ++i) { v[i] = (f32x4){0.f, 0.f, 0.f, 0.f}; if (okc) v[i] = *(const f32x4*)(t.W + (size_t)(t.k0 + 4 * i + kq) * t.N + t.n0 + c4); }
; }
;     ...
;     for (; it < it1; it += NGW) {
;         const bool more = it + NGW < it1;
;         if (more) { TR_DESCRIBE(it + NGW, tn); tr_load(tn, vn, lane); }
.LBB0_72:
	s_or_b64 exec, exec, s[30:31]
	v_mov_b32_e32 v68, v66
	v_mov_b32_e32 v69, v66
	v_mov_b32_e32 v67, v66
	v_mov_b64_e32 v[104:105], v[68:69]
	v_mov_b64_e32 v[108:109], v[68:69]
	v_mov_b64_e32 v[102:103], v[66:67]
	v_mov_b64_e32 v[106:107], v[66:67]
	s_and_saveexec_b64 s[30:31], vcc
	s_cbranch_execz .LBB0_74
	v_add_u32_e32 v102, s41, v147
	v_ashrrev_i32_e32 v105, 31, v102
	v_mad_u64_u32 v[102:103], s[46:47], s43, v102, 0
	v_mov_b32_e32 v104, v103
	v_mad_u64_u32 v[104:105], s[46:47], s43, v105, v[104:105]
	v_mov_b32_e32 v103, v104
	v_add_u32_e32 v104, s41, v148
	v_ashrrev_i32_e32 v107, 31, v104
	v_mad_u64_u32 v[104:105], s[48:49], s43, v104, 0
	v_mov_b32_e32 v106, v105
	v_mad_u64_u32 v[106:107], s[48:49], s43, v107, v[106:107]
	s_ashr_i32 s21, s20, 31
	v_mov_b32_e32 v105, v106
	v_lshl_add_u64 v[102:103], v[102:103], 2, s[28:29]
	s_lshl_b64 s[46:47], s[20:21], 2
	v_lshl_add_u64 v[104:105], v[104:105], 2, s[28:29]
	v_lshl_add_u64 v[102:103], v[102:103], 0, s[46:47]
	v_mov_b32_e32 v135, v66
	v_lshl_add_u64 v[104:105], v[104:105], 0, s[46:47]
	v_lshl_add_u64 v[102:103], v[102:103], 0, v[134:135]
	v_lshl_add_u64 v[104:105], v[104:105], 0, v[134:135]
	global_load_dwordx4 v[106:109], v[102:103], off nt
	s_nop 0
	global_load_dwordx4 v[102:105], v[104:105], off nt
.LBB0_74:
	s_or_b64 exec, exec, s[30:31]
	v_mov_b64_e32 v[112:113], v[68:69]
	v_mov_b64_e32 v[116:117], v[68:69]
	v_mov_b64_e32 v[110:111], v[66:67]
	v_mov_b64_e32 v[114:115], v[66:67]
	s_and_saveexec_b64 s[30:31], vcc
	s_cbranch_execz .LBB0_76
	v_add_u32_e32 v67, s41, v149
	v_mad_u64_u32 v[68:69], s[46:47], s43, v67, 0
	v_ashrrev_i32_e32 v111, 31, v67
	v_mov_b32_e32 v110, v69
	v_mad_u64_u32 v[110:111], s[46:47], s43, v111, v[110:111]
	v_add_u32_e32 v67, s41, v150
	v_mov_b32_e32 v69, v110
	v_mad_u64_u32 v[110:111], s[48:49], s43, v67, 0
	v_ashrrev_i32_e32 v113, 31, v67
	v_mov_b32_e32 v112, v111
	v_mad_u64_u32 v[112:113], s[48:49], s43, v113, v[112:113]
	s_ashr_i32 s21, s20, 31
	v_mov_b32_e32 v111, v112
	v_lshl_add_u64 v[68:69], v[68:69], 2, s[28:29]
	s_lshl_b64 s[46:47], s[20:21], 2
	v_lshl_add_u64 v[110:111], v[110:111], 2, s[28:29]
	v_lshl_add_u64 v[68:69], v[68:69], 0, s[46:47]
	v_mov_b32_e32 v135, v66
	v_lshl_add_u64 v[110:111], v[110:111], 0, s[46:47]
	v_lshl_add_u64 v[68:69], v[68:69], 0, v[134:135]
	v_lshl_add_u64 v[110:111], v[110:111], 0, v[134:135]
	global_load_dwordx4 v[114:117], v[68:69], off nt
	s_nop 0
	global_load_dwordx4 v[110:113], v[110:111], off nt
.LBB0_76:
	s_or_b64 exec, exec, s[30:31]
	v_mov_b32_e32 v68, v66
	v_mov_b32_e32 v69, v66
	v_mov_b32_e32 v67, v66
	v_mov_b64_e32 v[120:121], v[68:69]
	v_mov_b64_e32 v[124:125], v[68:69]
	v_mov_b64_e32 v[118:119], v[66:67]
	v_mov_b64_e32 v[122:123], v[66:67]
	s_and_saveexec_b64 s[30:31], vcc
	s_cbranch_execz .LBB0_78
	v_add_u32_e32 v118, s41, v151
	v_ashrrev_i32_e32 v121, 31, v118
	v_mad_u64_u32 v[118:119], s[46:47], s43, v118, 0
	v_mov_b32_e32 v120, v119
	v_mad_u64_u32 v[120:121], s[46:47], s43, v121, v[120:121]
	v_mov_b32_e32 v119, v120
	v_add_u32_e32 v120, s41, v152
	v_ashrrev_i32_e32 v123, 31, v120
	v_mad_u64_u32 v[120:121], s[48:49], s43, v120, 0
	v_mov_b32_e32 v122, v121
	v_mad_u64_u32 v[122:123], s[48:49], s43, v123, v[122:123]
	s_ashr_i32 s21, s20, 31
	v_mov_b32_e32 v121, v122
	v_lshl_add_u64 v[118:119], v[118:119], 2, s[28:29]
	s_lshl_b64 s[46:47], s[20:21], 2
	v_lshl_add_u64 v[120:121], v[120:121], 2, s[28:29]
	v_lshl_add_u64 v[118:119], v[118:119], 0, s[46:47]
	v_mov_b32_e32 v135, v66
	v_lshl_add_u64 v[120:121], v[120:121], 0, s[46:47]
	v_lshl_add_u64 v[118:119], v[118:119], 0, v[134:135]
	v_lshl_add_u64 v[120:121], v[120:121], 0, v[134:135]
	global_load_dwordx4 v[122:125], v[118:119], off nt
	s_nop 0
	global_load_dwordx4 v[118:121], v[120:121], off nt
.LBB0_78:
	s_or_b64 exec, exec, s[30:31]
	v_mov_b64_e32 v[128:129], v[68:69]
	v_mov_b64_e32 v[132:133], v[68:69]
	v_mov_b64_e32 v[126:127], v[66:67]
	v_mov_b64_e32 v[130:131], v[66:67]
	s_and_saveexec_b64 s[30:31], vcc
	s_cbranch_execz .LBB0_80
	v_add_u32_e32 v67, s41, v153
	v_mad_u64_u32 v[68:69], s[46:47], s43, v67, 0
	v_ashrrev_i32_e32 v127, 31, v67
	v_mov_b32_e32 v126, v69
	v_mad_u64_u32 v[126:127], s[46:47], s43, v127, v[126:127]
	v_add_u32_e32 v67, s41, v154
	v_mov_b32_e32 v69, v126
	v_mad_u64_u32 v[126:127], s[48:49], s43, v67, 0
	v_ashrrev_i32_e32 v129, 31, v67
	v_mov_b32_e32 v128, v127
	v_mad_u64_u32 v[128:129], s[48:49], s43, v129, v[128:129]
	s_ashr_i32 s21, s20, 31
	v_mov_b32_e32 v127, v128
	v_lshl_add_u64 v[68:69], v[68:69], 2, s[28:29]
	s_lshl_b64 s[46:47], s[20:21], 2
	v_lshl_add_u64 v[126:127], v[126:127], 2, s[28:29]
	v_lshl_add_u64 v[68:69], v[68:69], 0, s[46:47]
	v_mov_b32_e32 v135, v66
	v_lshl_add_u64 v[126:127], v[126:127], 0, s[46:47]
	v_lshl_add_u64 v[68:69], v[68:69], 0, v[134:135]
	v_lshl_add_u64 v[130:131], v[126:127], 0, v[134:135]
	global_load_dwordx4 v[126:129], v[68:69], off nt
	s_nop 0
	global_load_dwordx4 v[130:133], v[130:131], off nt

; __device__ __forceinline__ void tr_load(const TrItem& t, f32x4 (&v)[16], int lane) {
;     const int c4 = 4 * (lane & 15), kq = lane >> 4; const bool okc = t.n0 + c4 < t.N;
; #pragma unroll
;     for (int i = 0; i < 16; ++i) { v[i] = (f32x4){0.f, 0.f, 0.f, 0.f}; if (okc) v[i] = *(const f32x4*)(t.W + (size_t)(t.k0 + 4 * i + kq) * t.N + t.n0 + c4); }
; }
.LBB0_304:
	s_mov_b32 s0, s26
	v_readlane_b32 s4, v252, 0
	s_sub_i32 s0, s0, s4
	v_readlane_b32 s1, v252, 6
	s_cmp_ge_u32 s0, s1
	v_readlane_b32 s5, v252, 1
	s_cbranch_scc1 .LBB0_348
	v_mov_b32_e32 v2, v0
	s_mov_b32 s0, s60
	v_readlane_b32 s1, v253, 1
	s_cmp_lt_i32 s0, s1
	v_readfirstlane_b32 s1, v2
	s_cbranch_scc1 .LBB0_348
	s_ashr_i32 s9, s1, 6
	v_readlane_b32 s1, v253, 1
	s_sub_i32 s0, s0, s1
	s_lshl_b32 s0, s0, 3
	s_add_i32 s18, s0, s9
	s_mov_b32 s0, 9
	s_ashr_i32 s1, s0, 31
	s_lshl_b64 s[0:1], s[0:1], 3
	v_readlane_b32 s4, v252, 2
	v_readlane_b32 s5, v252, 3
	s_add_u32 s0, s4, s0
	s_addc_u32 s1, s5, s1
	s_load_dwordx2 s[0:1], s[0:1], 0x0
	v_readlane_b32 s4, v253, 50
	s_mul_i32 s4, s4, 0x5800000
	v_readlane_b32 s5, v253, 51
	s_movk_i32 s92, 0x50
	s_waitcnt lgkmcnt(0)
	s_add_u32 s0, s0, s4
	s_mov_b32 s4, 10
	s_mov_b32 s4, 12
	s_addc_u32 s1, s1, 0
	s_lshl_b64 s[4:5], s[92:93], 20
	s_add_u32 s4, s78, s4
	s_movk_i32 s6, 0x7c
	s_addc_u32 s5, s79, s5
	v_and_b32_e32 v4, 63, v2
	s_movk_i32 s6, 0xa9
	s_cmpk_lt_i32 s18, 0xb00
	s_cselect_b64 s[10:11], -1, 0
	s_cmpk_gt_i32 s18, 0xaff
	v_lshrrev_b32_e32 v139, 4, v4
	s_cbranch_scc1 .LBB0_308
	s_mul_hi_i32 s6, s18, 0x2e8ba2e9
	s_lshr_b32 s7, s6, 31
	s_ashr_i32 s6, s6, 5
	s_add_i32 s7, s6, s7
	s_mul_i32 s6, s7, 0xb0
	s_sub_i32 s8, s18, s6
	s_lshl_b32 s6, s8, 6
	s_cmpk_gt_i32 s8, 0x57
	s_cselect_b32 s8, 0xffffea00, 0
	s_cselect_b32 s12, 0x80, 0
	s_add_i32 s8, s8, s6
	s_lshl_b32 s8, s8, 1
	s_and_b32 s13, s6, 64
	s_and_b32 s8, s8, 0xffffff00
	s_or_b32 s12, s13, s12
	s_or_b32 s19, s12, s8
	s_lshl_b32 s8, s7, 6
	v_or_b32_e32 v5, s8, v139
	v_mov_b64_e32 v[66:67], s[0:1]
	s_mov_b32 s16, 0xb000
	v_mad_i64_i32 v[6:7], s[12:13], v5, s16, v[66:67]
	s_ashr_i32 s7, s6, 31
	v_or_b32_e32 v10, 4, v5
	v_or_b32_e32 v14, 8, v5
	v_or_b32_e32 v18, 12, v5
	v_or_b32_e32 v22, 16, v5
	v_or_b32_e32 v26, 20, v5
	v_or_b32_e32 v30, 24, v5
	v_or_b32_e32 v34, 28, v5
	v_or_b32_e32 v38, 32, v5
	v_or_b32_e32 v42, 36, v5
	v_or_b32_e32 v46, 40, v5
	v_or_b32_e32 v50, 44, v5
	v_or_b32_e32 v54, 48, v5
	v_or_b32_e32 v58, 52, v5
	v_or_b32_e32 v62, 56, v5
	v_or_b32_e32 v5, 60, v5
	s_lshl_b64 s[12:13], s[6:7], 2
	v_lshlrev_b32_e32 v2, 4, v4
	v_mad_i64_i32 v[10:11], s[14:15], v10, s16, v[66:67]
	v_mad_i64_i32 v[14:15], s[14:15], v14, s16, v[66:67]
	v_mad_i64_i32 v[18:19], s[14:15], v18, s16, v[66:67]
	v_mad_i64_i32 v[22:23], s[14:15], v22, s16, v[66:67]
	v_mad_i64_i32 v[26:27], s[14:15], v26, s16, v[66:67]
	v_mad_i64_i32 v[30:31], s[14:15], v30, s16, v[66:67]
	v_mad_i64_i32 v[34:35], s[14:15], v34, s16, v[66:67]
	v_mad_i64_i32 v[38:39], s[14:15], v38, s16, v[66:67]
	v_mad_i64_i32 v[42:43], s[14:15], v42, s16, v[66:67]
	v_mad_i64_i32 v[46:47], s[14:15], v46, s16, v[66:67]
	v_mad_i64_i32 v[50:51], s[14:15], v50, s16, v[66:67]
	v_mad_i64_i32 v[54:55], s[14:15], v54, s16, v[66:67]
	v_mad_i64_i32 v[58:59], s[14:15], v58, s16, v[66:67]
	v_mad_i64_i32 v[62:63], s[14:15], v62, s16, v[66:67]
	v_mad_i64_i32 v[66:67], s[14:15], v5, s16, v[66:67]
	v_lshl_add_u64 v[6:7], v[6:7], 0, s[12:13]
	v_and_b32_e32 v2, 0xf0, v2
	v_lshl_add_u64 v[10:11], v[10:11], 0, s[12:13]
	v_lshl_add_u64 v[14:15], v[14:15], 0, s[12:13]
	v_lshl_add_u64 v[18:19], v[18:19], 0, s[12:13]
	v_lshl_add_u64 v[22:23], v[22:23], 0, s[12:13]
	v_lshl_add_u64 v[26:27], v[26:27], 0, s[12:13]
	v_lshl_add_u64 v[30:31], v[30:31], 0, s[12:13]
	v_lshl_add_u64 v[34:35], v[34:35], 0, s[12:13]
	v_lshl_add_u64 v[38:39], v[38:39], 0, s[12:13]
	v_lshl_add_u64 v[42:43], v[42:43], 0, s[12:13]
	v_lshl_add_u64 v[46:47], v[46:47], 0, s[12:13]
	v_lshl_add_u64 v[50:51], v[50:51], 0, s[12:13]
	v_lshl_add_u64 v[54:55], v[54:55], 0, s[12:13]
	v_lshl_add_u64 v[58:59], v[58:59], 0, s[12:13]
	v_lshl_add_u64 v[62:63], v[62:63], 0, s[12:13]
	v_lshl_add_u64 v[66:67], v[66:67], 0, s[12:13]
	v_lshl_add_u64 v[6:7], v[6:7], 0, v[2:3]
	v_lshl_add_u64 v[10:11], v[10:11], 0, v[2:3]
	v_lshl_add_u64 v[14:15], v[14:15], 0, v[2:3]
	v_lshl_add_u64 v[18:19], v[18:19], 0, v[2:3]
	v_lshl_add_u64 v[22:23], v[22:23], 0, v[2:3]
	v_lshl_add_u64 v[26:27], v[26:27], 0, v[2:3]
	v_lshl_add_u64 v[30:31], v[30:31], 0, v[2:3]
	v_lshl_add_u64 v[34:35], v[34:35], 0, v[2:3]
	v_lshl_add_u64 v[38:39], v[38:39], 0, v[2:3]
	v_lshl_add_u64 v[42:43], v[42:43], 0, v[2:3]
	v_lshl_add_u64 v[46:47], v[46:47], 0, v[2:3]
	v_lshl_add_u64 v[50:51], v[50:51], 0, v[2:3]
	v_lshl_add_u64 v[54:55], v[54:55], 0, v[2:3]
	v_lshl_add_u64 v[58:59], v[58:59], 0, v[2:3]
	v_lshl_add_u64 v[62:63], v[62:63], 0, v[2:3]
	v_lshl_add_u64 v[66:67], v[66:67], 0, v[2:3]
	global_load_dwordx4 v[6:9], v[6:7], off nt
	s_nop 0
	global_load_dwordx4 v[10:13], v[10:11], off nt
	s_nop 0
	global_load_dwordx4 v[14:17], v[14:15], off nt
	s_nop 0
	global_load_dwordx4 v[18:21], v[18:19], off nt
	s_nop 0
	global_load_dwordx4 v[22:25], v[22:23], off nt
	s_nop 0
	global_load_dwordx4 v[26:29], v[26:27], off nt
	s_nop 0
	global_load_dwordx4 v[30:33], v[30:31], off nt
	s_nop 0
	global_load_dwordx4 v[34:37], v[34:35], off nt
	s_nop 0
	global_load_dwordx4 v[38:41], v[38:39], off nt
	s_nop 0
	global_load_dwordx4 v[42:45], v[42:43], off nt
	s_nop 0
	global_load_dwordx4 v[46:49], v[46:47], off nt
	s_nop 0
	global_load_dwordx4 v[50:53], v[50:51], off nt
	s_nop 0
	global_load_dwordx4 v[54:57], v[54:55], off nt
	s_nop 0
	global_load_dwordx4 v[58:61], v[58:59], off nt
	s_nop 0
	global_load_dwordx4 v[62:65], v[62:63], off nt
	s_nop 0
	global_load_dwordx4 v[66:69], v[66:67], off nt

; __device__ __forceinline__ void tr_load(const TrItem& t, f32x4 (&v)[16], int lane) {
;     const int c4 = 4 * (lane & 15), kq = lane >> 4; const bool okc = t.n0 + c4 < t.N;
; #pragma unroll
;     for (int i = 0; i < 16; ++i) { v[i] = (f32x4){0.f, 0.f, 0.f, 0.f}; if (okc) v[i] = *(const f32x4*)(t.W + (size_t)(t.k0 + 4 * i + kq) * t.N + t.n0 + c4); }
; }
;     ...
;     for (; it < it1; it += NGW) {
;         const bool more = it + NGW < it1;
;         if (more) { TR_DESCRIBE(it + NGW, tn); tr_load(tn, vn, lane); }
.LBB0_311:
	s_waitcnt vmcnt(0)
	s_add_i32 s18, s18, s27
	s_cmpk_lt_i32 s18, 0xb00
	s_cselect_b64 s[14:15], -1, 0
	s_cmpk_gt_i32 s18, 0xaff
	s_cselect_b64 s[12:13], -1, 0
	s_and_b64 vcc, exec, s[12:13]
	s_cbranch_vccnz .LBB0_329
	s_mul_hi_i32 s9, s18, 0x2e8ba2e9
	s_lshr_b32 s10, s9, 31
	s_ashr_i32 s22, s9, 5
	s_add_i32 s22, s22, s10
	s_mul_i32 s9, s22, 0xffffd400
	s_add_i32 s10, s7, s9
	v_mov_b32_e32 v72, v3
	v_mov_b32_e32 v73, v3
	v_add_u32_e32 v2, s10, v138
	v_mov_b32_e32 v70, v3
	v_mov_b32_e32 v71, v3
	v_mov_b64_e32 v[76:77], v[72:73]
	v_mov_b64_e32 v[80:81], v[72:73]
	s_lshl_b32 s21, s22, 6
	v_cmp_gt_i32_e32 vcc, s30, v2
	v_lshlrev_b32_e32 v134, 2, v138
	v_mov_b64_e32 v[74:75], v[70:71]
	v_mov_b64_e32 v[78:79], v[70:71]
	s_and_saveexec_b64 s[16:17], vcc
	s_cbranch_execz .LBB0_314
	v_or_b32_e32 v2, s21, v139
	v_mov_b64_e32 v[4:5], s[0:1]
	v_mad_i64_i32 v[74:75], s[24:25], v2, s31, v[4:5]
	s_ashr_i32 s11, s10, 31
	s_lshl_b64 s[24:25], s[10:11], 2
	v_or_b32_e32 v2, 4, v2
	v_lshl_add_u64 v[74:75], v[74:75], 0, s[24:25]
	v_mov_b32_e32 v135, v3
	v_mad_i64_i32 v[4:5], s[28:29], v2, s31, v[4:5]
	v_lshl_add_u64 v[74:75], v[74:75], 0, v[134:135]
	v_lshl_add_u64 v[4:5], v[4:5], 0, s[24:25]
	v_lshl_add_u64 v[4:5], v[4:5], 0, v[134:135]
	global_load_dwordx4 v[78:81], v[74:75], off nt
	s_nop 0
	global_load_dwordx4 v[74:77], v[4:5], off nt
.LBB0_314:
	s_or_b64 exec, exec, s[16:17]
	v_mov_b64_e32 v[84:85], v[72:73]
	v_or_b32_e32 v136, s21, v139
	v_mov_b64_e32 v[82:83], v[70:71]
	s_and_saveexec_b64 s[16:17], vcc
	s_cbranch_execz .LBB0_316
	v_or_b32_e32 v2, 8, v136
	v_mov_b64_e32 v[4:5], s[0:1]
	v_mad_i64_i32 v[70:71], s[24:25], v2, s31, v[4:5]
	s_ashr_i32 s11, s10, 31
	s_lshl_b64 s[24:25], s[10:11], 2
	v_or_b32_e32 v2, 12, v136
	v_lshl_add_u64 v[70:71], v[70:71], 0, s[24:25]
	v_mov_b32_e32 v135, v3
	v_mad_i64_i32 v[4:5], s[28:29], v2, s31, v[4:5]
	v_lshl_add_u64 v[70:71], v[70:71], 0, v[134:135]
	v_lshl_add_u64 v[4:5], v[4:5], 0, s[24:25]
	v_lshl_add_u64 v[4:5], v[4:5], 0, v[134:135]
	global_load_dwordx4 v[82:85], v[70:71], off nt
	s_nop 0
	global_load_dwordx4 v[70:73], v[4:5], off nt
.LBB0_316:
	s_or_b64 exec, exec, s[16:17]
	v_mov_b32_e32 v4, v3
	v_mov_b32_e32 v5, v3
	v_mov_b32_e32 v2, v3
	v_mov_b64_e32 v[88:89], v[4:5]
	v_mov_b64_e32 v[92:93], v[4:5]
	v_mov_b64_e32 v[86:87], v[2:3]
	v_mov_b64_e32 v[90:91], v[2:3]
	s_and_saveexec_b64 s[16:17], vcc
	s_cbranch_execz .LBB0_318
	v_or_b32_e32 v88, 16, v136
	v_mov_b64_e32 v[86:87], s[0:1]
	v_mad_i64_i32 v[88:89], s[24:25], v88, s31, v[86:87]
	s_ashr_i32 s11, s10, 31
	v_or_b32_e32 v90, 20, v136
	s_lshl_b64 s[24:25], s[10:11], 2
	v_mad_i64_i32 v[86:87], s[28:29], v90, s31, v[86:87]
	v_lshl_add_u64 v[88:89], v[88:89], 0, s[24:25]
	v_mov_b32_e32 v135, v3
	v_lshl_add_u64 v[86:87], v[86:87], 0, s[24:25]
	v_lshl_add_u64 v[88:89], v[88:89], 0, v[134:135]
	v_lshl_add_u64 v[86:87], v[86:87], 0, v[134:135]
	global_load_dwordx4 v[90:93], v[88:89], off nt
	s_nop 0
	global_load_dwordx4 v[86:89], v[86:87], off nt
.LBB0_318:
	s_or_b64 exec, exec, s[16:17]
	v_mov_b64_e32 v[96:97], v[4:5]
	v_mov_b64_e32 v[100:101], v[4:5]
	v_mov_b64_e32 v[94:95], v[2:3]
	v_mov_b64_e32 v[98:99], v[2:3]
	s_and_saveexec_b64 s[16:17], vcc
	s_cbranch_execz .LBB0_320
	v_or_b32_e32 v2, 24, v136
	v_mov_b64_e32 v[4:5], s[0:1]
	v_mad_i64_i32 v[94:95], s[24:25], v2, s31, v[4:5]
	s_ashr_i32 s11, s10, 31
	s_lshl_b64 s[24:25], s[10:11], 2
	v_or_b32_e32 v2, 28, v136
	v_lshl_add_u64 v[94:95], v[94:95], 0, s[24:25]
	v_mov_b32_e32 v135, v3
	v_mad_i64_i32 v[4:5], s[28:29], v2, s31, v[4:5]
	v_lshl_add_u64 v[94:95], v[94:95], 0, v[134:135]
	v_lshl_add_u64 v[4:5], v[4:5], 0, s[24:25]
	v_lshl_add_u64 v[4:5], v[4:5], 0, v[134:135]
	global_load_dwordx4 v[98:101], v[94:95], off nt
	s_nop 0
	global_load_dwordx4 v[94:97], v[4:5], off nt
; __device__ __forceinline__ void tr_load(const TrItem& t, f32x4 (&v)[16], int lane) {
;     const int c4 = 4 * (lane & 15), kq = lane >> 4; const bool okc = t.n0 + c4 < t.N;
; #pragma unroll
;     for (int i = 0; i < 16; ++i) { v[i] = (f32x4){0.f, 0.f, 0.f, 0.f}; if (okc) v[i] = *(const f32x4*)(t.W + (size_t)(t.k0 + 4 * i + kq) * t.N + t.n0 + c4); }
; }
.LBB0_320:
	s_or_b64 exec, exec, s[16:17]
	v_mov_b32_e32 v4, v3
	v_mov_b32_e32 v5, v3
	v_mov_b32_e32 v2, v3
	v_mov_b64_e32 v[104:105], v[4:5]
	v_mov_b64_e32 v[108:109], v[4:5]
	v_mov_b64_e32 v[102:103], v[2:3]
	v_mov_b64_e32 v[106:107], v[2:3]
	s_and_saveexec_b64 s[16:17], vcc
	s_cbranch_execz .LBB0_322
	v_or_b32_e32 v104, 32, v136
	v_mov_b64_e32 v[102:103], s[0:1]
	v_mad_i64_i32 v[104:105], s[24:25], v104, s31, v[102:103]
	s_ashr_i32 s11, s10, 31
	v_or_b32_e32 v106, 36, v136
	s_lshl_b64 s[24:25], s[10:11], 2
	v_mad_i64_i32 v[102:103], s[28:29], v106, s31, v[102:103]
	v_lshl_add_u64 v[104:105], v[104:105], 0, s[24:25]
	v_mov_b32_e32 v135, v3
	v_lshl_add_u64 v[102:103], v[102:103], 0, s[24:25]
	v_lshl_add_u64 v[104:105], v[104:105], 0, v[134:135]
	v_lshl_add_u64 v[102:103], v[102:103], 0, v[134:135]
	global_load_dwordx4 v[106:109], v[104:105], off nt
	s_nop 0
	global_load_dwordx4 v[102:105], v[102:103], off nt
.LBB0_322:
	s_or_b64 exec, exec, s[16:17]
	v_mov_b64_e32 v[112:113], v[4:5]
	v_mov_b64_e32 v[116:117], v[4:5]
	v_mov_b64_e32 v[110:111], v[2:3]
	v_mov_b64_e32 v[114:115], v[2:3]
	s_and_saveexec_b64 s[16:17], vcc
	s_cbranch_execz .LBB0_324
	v_or_b32_e32 v2, 40, v136
	v_mov_b64_e32 v[4:5], s[0:1]
	v_mad_i64_i32 v[110:111], s[24:25], v2, s31, v[4:5]
	s_ashr_i32 s11, s10, 31
	s_lshl_b64 s[24:25], s[10:11], 2
	v_or_b32_e32 v2, 44, v136
	v_lshl_add_u64 v[110:111], v[110:111], 0, s[24:25]
	v_mov_b32_e32 v135, v3
	v_mad_i64_i32 v[4:5], s[28:29], v2, s31, v[4:5]
	v_lshl_add_u64 v[110:111], v[110:111], 0, v[134:135]
	v_lshl_add_u64 v[4:5], v[4:5], 0, s[24:25]
	v_lshl_add_u64 v[4:5], v[4:5], 0, v[134:135]
	global_load_dwordx4 v[114:117], v[110:111], off nt
	s_nop 0
	global_load_dwordx4 v[110:113], v[4:5], off nt
.LBB0_324:
	s_or_b64 exec, exec, s[16:17]
	v_mov_b32_e32 v4, v3
	v_mov_b32_e32 v5, v3
	v_mov_b32_e32 v2, v3
	v_mov_b64_e32 v[120:121], v[4:5]
	v_mov_b64_e32 v[124:125], v[4:5]
	v_mov_b64_e32 v[118:119], v[2:3]
	v_mov_b64_e32 v[122:123], v[2:3]
	s_and_saveexec_b64 s[16:17], vcc
	s_cbranch_execz .LBB0_326
	v_or_b32_e32 v120, 48, v136
	v_mov_b64_e32 v[118:119], s[0:1]
	v_mad_i64_i32 v[120:121], s[24:25], v120, s31, v[118:119]
	s_ashr_i32 s11, s10, 31
	v_or_b32_e32 v122, 52, v136
	s_lshl_b64 s[24:25], s[10:11], 2
	v_mad_i64_i32 v[118:119], s[28:29], v122, s31, v[118:119]
	v_lshl_add_u64 v[120:121], v[120:121], 0, s[24:25]
	v_mov_b32_e32 v135, v3
	v_lshl_add_u64 v[118:119], v[118:119], 0, s[24:25]
	v_lshl_add_u64 v[120:121], v[120:121], 0, v[134:135]
	v_lshl_add_u64 v[118:119], v[118:119], 0, v[134:135]
	global_load_dwordx4 v[122:125], v[120:121], off nt
	s_nop 0
	global_load_dwordx4 v[118:121], v[118:119], off nt
.LBB0_326:
	s_or_b64 exec, exec, s[16:17]
	s_mulk_i32 s22, 0xff50
	s_add_i32 s11, s18, s22
	s_cmpk_gt_i32 s11, 0x57
	v_mov_b64_e32 v[128:129], v[4:5]
	v_mov_b64_e32 v[132:133], v[4:5]
	s_cselect_b32 s23, 0xffffea00, 0
	s_cselect_b32 s22, 0x80, 0
	v_mov_b64_e32 v[126:127], v[2:3]
	v_mov_b64_e32 v[130:131], v[2:3]
	s_and_saveexec_b64 s[16:17], vcc
	s_cbranch_execz .LBB0_328
	v_or_b32_e32 v2, 56, v136
	v_mov_b64_e32 v[4:5], s[0:1]
	v_mad_i64_i32 v[126:127], s[24:25], v2, s31, v[4:5]
	s_ashr_i32 s11, s10, 31
	s_lshl_b64 s[24:25], s[10:11], 2
	v_or_b32_e32 v2, 60, v136
	v_lshl_add_u64 v[126:127], v[126:127], 0, s[24:25]
	v_mov_b32_e32 v135, v3
	v_mad_i64_i32 v[4:5], s[28:29], v2, s31, v[4:5]
	v_lshl_add_u64 v[126:127], v[126:127], 0, v[134:135]
	v_lshl_add_u64 v[4:5], v[4:5], 0, s[24:25]
	v_lshl_add_u64 v[4:5], v[4:5], 0, v[134:135]
	global_load_dwordx4 v[126:129], v[126:127], off nt
	s_nop 0
	global_load_dwordx4 v[130:133], v[4:5], off nt

; __device__ __forceinline__ void tr_load(const TrItem& t, f32x4 (&v)[16], int lane) {
;     const int c4 = 4 * (lane & 15), kq = lane >> 4; const bool okc = t.n0 + c4 < t.N;
; #pragma unroll
;     for (int i = 0; i < 16; ++i) { v[i] = (f32x4){0.f, 0.f, 0.f, 0.f}; if (okc) v[i] = *(const f32x4*)(t.W + (size_t)(t.k0 + 4 * i + kq) * t.N + t.n0 + c4); }
; }
;     ...
;     int it = it0 + gw;
;     if (it < it1) { TR_DESCRIBE(it, tc); tr_load(tc, vc, lane); }
.LBB0_448:
	v_lshlrev_b32_e32 v2, 2, v72
	v_and_b32_e32 v6, 60, v2
	v_lshrrev_b32_e32 v7, 4, v72
	v_or_b32_e32 v2, s18, v6
	v_mov_b32_e32 v4, v3
	v_mov_b32_e32 v5, v3
	v_cmp_gt_i32_e32 vcc, s37, v2
	v_mov_b32_e32 v2, v3
	v_add_u32_e32 v73, s14, v7
	v_lshlrev_b32_e32 v70, 2, v6
	v_mov_b64_e32 v[12:13], v[4:5]
	v_mov_b64_e32 v[8:9], v[4:5]
	v_mov_b64_e32 v[10:11], v[2:3]
	v_mov_b64_e32 v[6:7], v[2:3]
	s_and_saveexec_b64 s[24:25], vcc
	s_cbranch_execz .LBB0_450
	v_add_u32_e32 v8, 4, v73
	v_mad_i64_i32 v[6:7], s[26:27], s37, v73, 0
	s_ashr_i32 s19, s18, 31
	v_mad_i64_i32 v[8:9], s[28:29], s37, v8, 0
	v_lshl_add_u64 v[6:7], v[6:7], 2, s[22:23]
	s_lshl_b64 s[26:27], s[18:19], 2
	v_lshl_add_u64 v[8:9], v[8:9], 2, s[22:23]
	v_lshl_add_u64 v[6:7], v[6:7], 0, s[26:27]
	v_mov_b32_e32 v71, v3
	v_lshl_add_u64 v[8:9], v[8:9], 0, s[26:27]
	v_lshl_add_u64 v[6:7], v[6:7], 0, v[70:71]
	v_lshl_add_u64 v[10:11], v[8:9], 0, v[70:71]
	global_load_dwordx4 v[6:9], v[6:7], off nt
	s_nop 0
	global_load_dwordx4 v[10:13], v[10:11], off nt
.LBB0_450:
	s_or_b64 exec, exec, s[24:25]
	v_mov_b64_e32 v[20:21], v[4:5]
	v_mov_b64_e32 v[16:17], v[4:5]
	v_mov_b64_e32 v[18:19], v[2:3]
	v_mov_b64_e32 v[14:15], v[2:3]
	s_and_saveexec_b64 s[24:25], vcc
	s_cbranch_execz .LBB0_452
	v_add_u32_e32 v2, 8, v73
	v_mad_i64_i32 v[4:5], s[26:27], s37, v2, 0
	v_add_u32_e32 v2, 12, v73
	s_ashr_i32 s19, s18, 31
	v_mad_i64_i32 v[14:15], s[28:29], s37, v2, 0
	v_lshl_add_u64 v[4:5], v[4:5], 2, s[22:23]
	s_lshl_b64 s[26:27], s[18:19], 2
	v_lshl_add_u64 v[14:15], v[14:15], 2, s[22:23]
	v_lshl_add_u64 v[4:5], v[4:5], 0, s[26:27]
	v_mov_b32_e32 v71, v3
	v_lshl_add_u64 v[14:15], v[14:15], 0, s[26:27]
	v_lshl_add_u64 v[4:5], v[4:5], 0, v[70:71]
	v_lshl_add_u64 v[18:19], v[14:15], 0, v[70:71]
	global_load_dwordx4 v[14:17], v[4:5], off nt
	s_nop 0
	global_load_dwordx4 v[18:21], v[18:19], off nt
.LBB0_452:
	s_or_b64 exec, exec, s[24:25]
	v_mov_b32_e32 v4, v3
	v_mov_b32_e32 v5, v3
	v_mov_b32_e32 v2, v3
	v_mov_b64_e32 v[28:29], v[4:5]
	v_mov_b64_e32 v[24:25], v[4:5]
	v_mov_b64_e32 v[26:27], v[2:3]
	v_mov_b64_e32 v[22:23], v[2:3]
	s_and_saveexec_b64 s[24:25], vcc
	s_cbranch_execz .LBB0_454
	v_add_u32_e32 v22, 16, v73
	v_add_u32_e32 v24, 20, v73
	v_mad_i64_i32 v[22:23], s[26:27], s37, v22, 0
	s_ashr_i32 s19, s18, 31
	v_mad_i64_i32 v[24:25], s[28:29], s37, v24, 0
	v_lshl_add_u64 v[22:23], v[22:23], 2, s[22:23]
	s_lshl_b64 s[26:27], s[18:19], 2
	v_lshl_add_u64 v[24:25], v[24:25], 2, s[22:23]
	v_lshl_add_u64 v[22:23], v[22:23], 0, s[26:27]
	v_mov_b32_e32 v71, v3
	v_lshl_add_u64 v[24:25], v[24:25], 0, s[26:27]
	v_lshl_add_u64 v[22:23], v[22:23], 0, v[70:71]
	v_lshl_add_u64 v[26:27], v[24:25], 0, v[70:71]
	global_load_dwordx4 v[22:25], v[22:23], off nt
	s_nop 0
	global_load_dwordx4 v[26:29], v[26:27], off nt
.LBB0_454:
	s_or_b64 exec, exec, s[24:25]
	v_mov_b64_e32 v[36:37], v[4:5]
	v_mov_b64_e32 v[32:33], v[4:5]
	v_mov_b64_e32 v[34:35], v[2:3]
	v_mov_b64_e32 v[30:31], v[2:3]
	s_and_saveexec_b64 s[24:25], vcc
	s_cbranch_execz .LBB0_456
	v_add_u32_e32 v2, 24, v73
	v_mad_i64_i32 v[4:5], s[26:27], s37, v2, 0
	v_add_u32_e32 v2, 28, v73
	s_ashr_i32 s19, s18, 31
	v_mad_i64_i32 v[30:31], s[28:29], s37, v2, 0
	v_lshl_add_u64 v[4:5], v[4:5], 2, s[22:23]
	s_lshl_b64 s[26:27], s[18:19], 2
	v_lshl_add_u64 v[30:31], v[30:31], 2, s[22:23]
	v_lshl_add_u64 v[4:5], v[4:5], 0, s[26:27]
	v_mov_b32_e32 v71, v3
	v_lshl_add_u64 v[30:31], v[30:31], 0, s[26:27]
	v_lshl_add_u64 v[4:5], v[4:5], 0, v[70:71]
	v_lshl_add_u64 v[34:35], v[30:31], 0, v[70:71]
	global_load_dwordx4 v[30:33], v[4:5], off nt
	s_nop 0
	global_load_dwordx4 v[34:37], v[34:35], off nt
; __device__ __forceinline__ void tr_load(const TrItem& t, f32x4 (&v)[16], int lane) {
;     const int c4 = 4 * (lane & 15), kq = lane >> 4; const bool okc = t.n0 + c4 < t.N;
; #pragma unroll
;     for (int i = 0; i < 16; ++i) { v[i] = (f32x4){0.f, 0.f, 0.f, 0.f}; if (okc) v[i] = *(const f32x4*)(t.W + (size_t)(t.k0 + 4 * i + kq) * t.N + t.n0 + c4); }
; }
.LBB0_456:
	s_or_b64 exec, exec, s[24:25]
	v_mov_b32_e32 v4, v3
	v_mov_b32_e32 v5, v3
	v_mov_b32_e32 v2, v3
	v_mov_b64_e32 v[44:45], v[4:5]
	v_mov_b64_e32 v[40:41], v[4:5]
	v_mov_b64_e32 v[42:43], v[2:3]
	v_mov_b64_e32 v[38:39], v[2:3]
	s_and_saveexec_b64 s[24:25], vcc
	s_cbranch_execz .LBB0_458
	v_add_u32_e32 v38, 32, v73
	v_add_u32_e32 v40, 36, v73
	v_mad_i64_i32 v[38:39], s[26:27], s37, v38, 0
	s_ashr_i32 s19, s18, 31
	v_mad_i64_i32 v[40:41], s[28:29], s37, v40, 0
	v_lshl_add_u64 v[38:39], v[38:39], 2, s[22:23]
	s_lshl_b64 s[26:27], s[18:19], 2
	v_lshl_add_u64 v[40:41], v[40:41], 2, s[22:23]
	v_lshl_add_u64 v[38:39], v[38:39], 0, s[26:27]
	v_mov_b32_e32 v71, v3
	v_lshl_add_u64 v[40:41], v[40:41], 0, s[26:27]
	v_lshl_add_u64 v[38:39], v[38:39], 0, v[70:71]
	v_lshl_add_u64 v[42:43], v[40:41], 0, v[70:71]
	global_load_dwordx4 v[38:41], v[38:39], off nt
	s_nop 0
	global_load_dwordx4 v[42:45], v[42:43], off nt
.LBB0_458:
	s_or_b64 exec, exec, s[24:25]
	v_mov_b64_e32 v[52:53], v[4:5]
	v_mov_b64_e32 v[48:49], v[4:5]
	v_mov_b64_e32 v[50:51], v[2:3]
	v_mov_b64_e32 v[46:47], v[2:3]
	s_and_saveexec_b64 s[24:25], vcc
	s_cbranch_execz .LBB0_460
	v_add_u32_e32 v2, 40, v73
	v_mad_i64_i32 v[4:5], s[26:27], s37, v2, 0
	v_add_u32_e32 v2, 44, v73
	s_ashr_i32 s19, s18, 31
	v_mad_i64_i32 v[46:47], s[28:29], s37, v2, 0
	v_lshl_add_u64 v[4:5], v[4:5], 2, s[22:23]
	s_lshl_b64 s[26:27], s[18:19], 2
	v_lshl_add_u64 v[46:47], v[46:47], 2, s[22:23]
	v_lshl_add_u64 v[4:5], v[4:5], 0, s[26:27]
	v_mov_b32_e32 v71, v3
	v_lshl_add_u64 v[46:47], v[46:47], 0, s[26:27]
	v_lshl_add_u64 v[4:5], v[4:5], 0, v[70:71]
	v_lshl_add_u64 v[50:51], v[46:47], 0, v[70:71]
	global_load_dwordx4 v[46:49], v[4:5], off nt
	s_nop 0
	global_load_dwordx4 v[50:53], v[50:51], off nt
.LBB0_460:
	s_or_b64 exec, exec, s[24:25]
	v_mov_b32_e32 v4, v3
	v_mov_b32_e32 v5, v3
	v_mov_b32_e32 v2, v3
	v_mov_b64_e32 v[60:61], v[4:5]
	v_mov_b64_e32 v[56:57], v[4:5]
	v_mov_b64_e32 v[58:59], v[2:3]
	v_mov_b64_e32 v[54:55], v[2:3]
	s_and_saveexec_b64 s[24:25], vcc
	s_cbranch_execz .LBB0_462
	v_add_u32_e32 v54, 48, v73
	v_add_u32_e32 v56, 52, v73
	v_mad_i64_i32 v[54:55], s[26:27], s37, v54, 0
	s_ashr_i32 s19, s18, 31
	v_mad_i64_i32 v[56:57], s[28:29], s37, v56, 0
	v_lshl_add_u64 v[54:55], v[54:55], 2, s[22:23]
	s_lshl_b64 s[26:27], s[18:19], 2
	v_lshl_add_u64 v[56:57], v[56:57], 2, s[22:23]
	v_lshl_add_u64 v[54:55], v[54:55], 0, s[26:27]
	v_mov_b32_e32 v71, v3
	v_lshl_add_u64 v[56:57], v[56:57], 0, s[26:27]
	v_lshl_add_u64 v[54:55], v[54:55], 0, v[70:71]
	v_lshl_add_u64 v[58:59], v[56:57], 0, v[70:71]
	global_load_dwordx4 v[54:57], v[54:55], off nt
	s_nop 0
	global_load_dwordx4 v[58:61], v[58:59], off nt
.LBB0_462:
	s_or_b64 exec, exec, s[24:25]
	v_mov_b64_e32 v[64:65], v[4:5]
	v_mov_b64_e32 v[68:69], v[4:5]
	v_mov_b64_e32 v[62:63], v[2:3]
	v_mov_b64_e32 v[66:67], v[2:3]
	s_and_saveexec_b64 s[24:25], vcc
	s_cbranch_execz .LBB0_464
	v_add_u32_e32 v2, 56, v73
	v_mad_i64_i32 v[4:5], s[26:27], s37, v2, 0
	v_add_u32_e32 v2, 60, v73
	s_ashr_i32 s19, s18, 31
	v_mad_i64_i32 v[62:63], s[28:29], s37, v2, 0
	v_lshl_add_u64 v[4:5], v[4:5], 2, s[22:23]
	s_lshl_b64 s[26:27], s[18:19], 2
	v_lshl_add_u64 v[62:63], v[62:63], 2, s[22:23]
	v_lshl_add_u64 v[4:5], v[4:5], 0, s[26:27]
	v_mov_b32_e32 v71, v3
	v_lshl_add_u64 v[62:63], v[62:63], 0, s[26:27]
	v_lshl_add_u64 v[4:5], v[4:5], 0, v[70:71]
	v_lshl_add_u64 v[66:67], v[62:63], 0, v[70:71]
	global_load_dwordx4 v[62:65], v[4:5], off nt
	s_nop 0
	global_load_dwordx4 v[66:69], v[66:67], off nt

; __device__ __forceinline__ void tr_load(const TrItem& t, f32x4 (&v)[16], int lane) {
;     const int c4 = 4 * (lane & 15), kq = lane >> 4; const bool okc = t.n0 + c4 < t.N;
; #pragma unroll
;     for (int i = 0; i < 16; ++i) { v[i] = (f32x4){0.f, 0.f, 0.f, 0.f}; if (okc) v[i] = *(const f32x4*)(t.W + (size_t)(t.k0 + 4 * i + kq) * t.N + t.n0 + c4); }
; }
;     ...
;     for (; it < it1; it += NGW) {
;         const bool more = it + NGW < it1;
;         if (more) { TR_DESCRIBE(it + NGW, tn); tr_load(tn, vn, lane); }
.LBB0_477:
	v_or_b32_e32 v2, s22, v138
	v_mov_b32_e32 v4, v3
	v_mov_b32_e32 v5, v3
	v_cmp_gt_i32_e32 vcc, s43, v2
	v_mov_b32_e32 v2, v3
	v_mov_b64_e32 v[72:73], v[4:5]
	v_mov_b64_e32 v[76:77], v[4:5]
	v_lshlrev_b32_e32 v134, 2, v138
	v_mov_b64_e32 v[70:71], v[2:3]
	v_mov_b64_e32 v[74:75], v[2:3]
	s_and_saveexec_b64 s[30:31], vcc
	s_cbranch_execz .LBB0_479
	v_add_u32_e32 v70, s41, v139
	v_add_u32_e32 v72, s41, v141
	v_mad_i64_i32 v[70:71], s[46:47], s43, v70, 0
	s_ashr_i32 s23, s22, 31
	v_mad_i64_i32 v[72:73], s[48:49], s43, v72, 0
	v_lshl_add_u64 v[70:71], v[70:71], 2, s[28:29]
	s_lshl_b64 s[46:47], s[22:23], 2
	v_lshl_add_u64 v[72:73], v[72:73], 2, s[28:29]
	v_lshl_add_u64 v[70:71], v[70:71], 0, s[46:47]
	v_mov_b32_e32 v135, v3
	v_lshl_add_u64 v[72:73], v[72:73], 0, s[46:47]
	v_lshl_add_u64 v[70:71], v[70:71], 0, v[134:135]
	v_lshl_add_u64 v[72:73], v[72:73], 0, v[134:135]
	global_load_dwordx4 v[74:77], v[70:71], off nt
	s_nop 0
	global_load_dwordx4 v[70:73], v[72:73], off nt
.LBB0_479:
	s_or_b64 exec, exec, s[30:31]
	v_mov_b64_e32 v[80:81], v[4:5]
	v_mov_b64_e32 v[84:85], v[4:5]
	v_mov_b64_e32 v[78:79], v[2:3]
	v_mov_b64_e32 v[82:83], v[2:3]
	s_and_saveexec_b64 s[30:31], vcc
	s_cbranch_execz .LBB0_481
	v_add_u32_e32 v2, s41, v142
	v_mad_i64_i32 v[4:5], s[46:47], s43, v2, 0
	v_add_u32_e32 v2, s41, v143
	s_ashr_i32 s23, s22, 31
	v_mad_i64_i32 v[78:79], s[48:49], s43, v2, 0
	v_lshl_add_u64 v[4:5], v[4:5], 2, s[28:29]
	s_lshl_b64 s[46:47], s[22:23], 2
	v_lshl_add_u64 v[78:79], v[78:79], 2, s[28:29]
	v_lshl_add_u64 v[4:5], v[4:5], 0, s[46:47]
	v_mov_b32_e32 v135, v3
	v_lshl_add_u64 v[78:79], v[78:79], 0, s[46:47]
	v_lshl_add_u64 v[4:5], v[4:5], 0, v[134:135]
	v_lshl_add_u64 v[78:79], v[78:79], 0, v[134:135]
	global_load_dwordx4 v[82:85], v[4:5], off nt
	s_nop 0
	global_load_dwordx4 v[78:81], v[78:79], off nt
.LBB0_481:
	s_or_b64 exec, exec, s[30:31]
	v_mov_b32_e32 v4, v3
	v_mov_b32_e32 v5, v3
	v_mov_b32_e32 v2, v3
	v_mov_b64_e32 v[88:89], v[4:5]
	v_mov_b64_e32 v[92:93], v[4:5]
	v_mov_b64_e32 v[86:87], v[2:3]
	v_mov_b64_e32 v[90:91], v[2:3]
	s_and_saveexec_b64 s[30:31], vcc
	s_cbranch_execz .LBB0_483
	v_add_u32_e32 v86, s41, v144
	v_add_u32_e32 v88, s41, v145
	v_mad_i64_i32 v[86:87], s[46:47], s43, v86, 0
	s_ashr_i32 s23, s22, 31
	v_mad_i64_i32 v[88:89], s[48:49], s43, v88, 0
	v_lshl_add_u64 v[86:87], v[86:87], 2, s[28:29]
	s_lshl_b64 s[46:47], s[22:23], 2
	v_lshl_add_u64 v[88:89], v[88:89], 2, s[28:29]
	v_lshl_add_u64 v[86:87], v[86:87], 0, s[46:47]
	v_mov_b32_e32 v135, v3
	v_lshl_add_u64 v[88:89], v[88:89], 0, s[46:47]
	v_lshl_add_u64 v[86:87], v[86:87], 0, v[134:135]
	v_lshl_add_u64 v[88:89], v[88:89], 0, v[134:135]
	global_load_dwordx4 v[90:93], v[86:87], off nt
	s_nop 0
	global_load_dwordx4 v[86:89], v[88:89], off nt
.LBB0_483:
	s_or_b64 exec, exec, s[30:31]
	v_mov_b64_e32 v[96:97], v[4:5]
	v_mov_b64_e32 v[100:101], v[4:5]
	v_mov_b64_e32 v[94:95], v[2:3]
	v_mov_b64_e32 v[98:99], v[2:3]
	s_and_saveexec_b64 s[30:31], vcc
	s_cbranch_execz .LBB0_485
	v_add_u32_e32 v2, s41, v146
	v_mad_i64_i32 v[4:5], s[46:47], s43, v2, 0
	v_add_u32_e32 v2, s41, v147
	s_ashr_i32 s23, s22, 31
	v_mad_i64_i32 v[94:95], s[48:49], s43, v2, 0
	v_lshl_add_u64 v[4:5], v[4:5], 2, s[28:29]
	s_lshl_b64 s[46:47], s[22:23], 2
	v_lshl_add_u64 v[94:95], v[94:95], 2, s[28:29]
	v_lshl_add_u64 v[4:5], v[4:5], 0, s[46:47]
	v_mov_b32_e32 v135, v3
	v_lshl_add_u64 v[94:95], v[94:95], 0, s[46:47]
	v_lshl_add_u64 v[4:5], v[4:5], 0, v[134:135]
	v_lshl_add_u64 v[94:95], v[94:95], 0, v[134:135]
	global_load_dwordx4 v[98:101], v[4:5], off nt
	s_nop 0
	global_load_dwordx4 v[94:97], v[94:95], off nt
; __device__ __forceinline__ void tr_load(const TrItem& t, f32x4 (&v)[16], int lane) {
;     const int c4 = 4 * (lane & 15), kq = lane >> 4; const bool okc = t.n0 + c4 < t.N;
; #pragma unroll
;     for (int i = 0; i < 16; ++i) { v[i] = (f32x4){0.f, 0.f, 0.f, 0.f}; if (okc) v[i] = *(const f32x4*)(t.W + (size_t)(t.k0 + 4 * i + kq) * t.N + t.n0 + c4); }
; }
;     ...
;     for (; it < it1; it += NGW) {
;         const bool more = it + NGW < it1;
;         if (more) { TR_DESCRIBE(it + NGW, tn); tr_load(tn, vn, lane); }
.LBB0_485:
	s_or_b64 exec, exec, s[30:31]
	v_mov_b32_e32 v4, v3
	v_mov_b32_e32 v5, v3
	v_mov_b32_e32 v2, v3
	v_mov_b64_e32 v[104:105], v[4:5]
	v_mov_b64_e32 v[108:109], v[4:5]
	v_mov_b64_e32 v[102:103], v[2:3]
	v_mov_b64_e32 v[106:107], v[2:3]
	s_and_saveexec_b64 s[30:31], vcc
	s_cbranch_execz .LBB0_487
	v_add_u32_e32 v102, s41, v148
	v_add_u32_e32 v104, s41, v149
	v_mad_i64_i32 v[102:103], s[46:47], s43, v102, 0
	s_ashr_i32 s23, s22, 31
	v_mad_i64_i32 v[104:105], s[48:49], s43, v104, 0
	v_lshl_add_u64 v[102:103], v[102:103], 2, s[28:29]
	s_lshl_b64 s[46:47], s[22:23], 2
	v_lshl_add_u64 v[104:105], v[104:105], 2, s[28:29]
	v_lshl_add_u64 v[102:103], v[102:103], 0, s[46:47]
	v_mov_b32_e32 v135, v3
	v_lshl_add_u64 v[104:105], v[104:105], 0, s[46:47]
	v_lshl_add_u64 v[102:103], v[102:103], 0, v[134:135]
	v_lshl_add_u64 v[104:105], v[104:105], 0, v[134:135]
	global_load_dwordx4 v[106:109], v[102:103], off nt
	s_nop 0
	global_load_dwordx4 v[102:105], v[104:105], off nt
.LBB0_487:
	s_or_b64 exec, exec, s[30:31]
	v_mov_b64_e32 v[112:113], v[4:5]
	v_mov_b64_e32 v[116:117], v[4:5]
	v_mov_b64_e32 v[110:111], v[2:3]
	v_mov_b64_e32 v[114:115], v[2:3]
	s_and_saveexec_b64 s[30:31], vcc
	s_cbranch_execz .LBB0_489
	v_add_u32_e32 v2, s41, v150
	v_mad_i64_i32 v[4:5], s[46:47], s43, v2, 0
	v_add_u32_e32 v2, s41, v151
	s_ashr_i32 s23, s22, 31
	v_mad_i64_i32 v[110:111], s[48:49], s43, v2, 0
	v_lshl_add_u64 v[4:5], v[4:5], 2, s[28:29]
	s_lshl_b64 s[46:47], s[22:23], 2
	v_lshl_add_u64 v[110:111], v[110:111], 2, s[28:29]
	v_lshl_add_u64 v[4:5], v[4:5], 0, s[46:47]
	v_mov_b32_e32 v135, v3
	v_lshl_add_u64 v[110:111], v[110:111], 0, s[46:47]
	v_lshl_add_u64 v[4:5], v[4:5], 0, v[134:135]
	v_lshl_add_u64 v[110:111], v[110:111], 0, v[134:135]
	global_load_dwordx4 v[114:117], v[4:5], off nt
	s_nop 0
	global_load_dwordx4 v[110:113], v[110:111], off nt
.LBB0_489:
	s_or_b64 exec, exec, s[30:31]
	v_mov_b32_e32 v4, v3
	v_mov_b32_e32 v5, v3
	v_mov_b32_e32 v2, v3
	v_mov_b64_e32 v[120:121], v[4:5]
	v_mov_b64_e32 v[124:125], v[4:5]
	v_mov_b64_e32 v[118:119], v[2:3]
	v_mov_b64_e32 v[122:123], v[2:3]
	s_and_saveexec_b64 s[30:31], vcc
	s_cbranch_execz .LBB0_491
	v_add_u32_e32 v118, s41, v152
	v_add_u32_e32 v120, s41, v153
	v_mad_i64_i32 v[118:119], s[46:47], s43, v118, 0
	s_ashr_i32 s23, s22, 31
	v_mad_i64_i32 v[120:121], s[48:49], s43, v120, 0
	v_lshl_add_u64 v[118:119], v[118:119], 2, s[28:29]
	s_lshl_b64 s[46:47], s[22:23], 2
	v_lshl_add_u64 v[120:121], v[120:121], 2, s[28:29]
	v_lshl_add_u64 v[118:119], v[118:119], 0, s[46:47]
	v_mov_b32_e32 v135, v3
	v_lshl_add_u64 v[120:121], v[120:121], 0, s[46:47]
	v_lshl_add_u64 v[118:119], v[118:119], 0, v[134:135]
	v_lshl_add_u64 v[120:121], v[120:121], 0, v[134:135]
	global_load_dwordx4 v[122:125], v[118:119], off nt
	s_nop 0
	global_load_dwordx4 v[118:121], v[120:121], off nt
.LBB0_491:
	s_or_b64 exec, exec, s[30:31]
	v_mov_b64_e32 v[128:129], v[4:5]
	v_mov_b64_e32 v[132:133], v[4:5]
	v_mov_b64_e32 v[126:127], v[2:3]
	v_mov_b64_e32 v[130:131], v[2:3]
	s_and_saveexec_b64 s[30:31], vcc
	s_cbranch_execz .LBB0_493
	v_add_u32_e32 v2, s41, v154
	v_mad_i64_i32 v[4:5], s[46:47], s43, v2, 0
	v_add_u32_e32 v2, s41, v155
	s_ashr_i32 s23, s22, 31
	v_mad_i64_i32 v[126:127], s[48:49], s43, v2, 0
	v_lshl_add_u64 v[4:5], v[4:5], 2, s[28:29]
	s_lshl_b64 s[46:47], s[22:23], 2
	v_lshl_add_u64 v[126:127], v[126:127], 2, s[28:29]
	v_lshl_add_u64 v[4:5], v[4:5], 0, s[46:47]
	v_mov_b32_e32 v135, v3
	v_lshl_add_u64 v[126:127], v[126:127], 0, s[46:47]
	v_lshl_add_u64 v[4:5], v[4:5], 0, v[134:135]
	v_lshl_add_u64 v[130:131], v[126:127], 0, v[134:135]
	global_load_dwordx4 v[126:129], v[4:5], off nt
	s_nop 0
	global_load_dwordx4 v[130:133], v[130:131], off nt

; __device__ __forceinline__ void tr_load(const TrItem& t, f32x4 (&v)[16], int lane) {
;     const int c4 = 4 * (lane & 15), kq = lane >> 4; const bool okc = t.n0 + c4 < t.N;
; #pragma unroll
;     for (int i = 0; i < 16; ++i) { v[i] = (f32x4){0.f, 0.f, 0.f, 0.f}; if (okc) v[i] = *(const f32x4*)(t.W + (size_t)(t.k0 + 4 * i + kq) * t.N + t.n0 + c4); }
; }
.LBB0_671:
	s_mov_b32 s0, s24
	v_readlane_b32 s2, v252, 0
	s_sub_i32 s0, s0, s2
	v_readlane_b32 s1, v252, 6
	s_cmp_ge_u32 s0, s1
	v_readlane_b32 s3, v252, 1
	s_cbranch_scc1 .LBB0_715
	v_mov_b32_e32 v2, v0
	s_mov_b32 s0, s60
	v_readlane_b32 s1, v253, 4
	s_cmp_lt_i32 s0, s1
	v_readfirstlane_b32 s1, v2
	s_cbranch_scc1 .LBB0_715
	s_ashr_i32 s7, s1, 6
	v_readlane_b32 s1, v253, 4
	s_sub_i32 s0, s0, s1
	s_lshl_b32 s0, s0, 3
	s_add_i32 s4, s0, s7
	s_mov_b32 s0, 9
	s_ashr_i32 s1, s0, 31
	s_lshl_b64 s[0:1], s[0:1], 3
	v_readlane_b32 s2, v252, 2
	v_readlane_b32 s3, v252, 3
	s_add_u32 s0, s2, s0
	s_addc_u32 s1, s3, s1
	s_load_dwordx2 s[0:1], s[0:1], 0x0
	v_readlane_b32 s2, v253, 50
	s_mul_i32 s2, s2, 0x5800000
	v_readlane_b32 s3, v253, 51
	s_movk_i32 s92, 0x50
	s_waitcnt lgkmcnt(0)
	s_add_u32 s0, s0, s2
	s_mov_b32 s2, 10
	s_mov_b32 s2, 12
	s_addc_u32 s1, s1, 0
	s_lshl_b64 s[2:3], s[92:93], 20
	s_add_u32 s2, s78, s2
	s_addc_u32 s3, s79, s3
	s_movk_i32 s5, 0x7c
	s_add_i32 s16, s4, 0xb00
	v_and_b32_e32 v4, 63, v2
	s_cmpk_lt_i32 s4, 0xb00
	s_movk_i32 s5, 0xa9
	s_cselect_b64 s[8:9], -1, 0
	s_cmpk_gt_i32 s4, 0xaff
	v_lshrrev_b32_e32 v139, 4, v4
	s_mov_b32 s28, 0xb000
	s_cbranch_scc1 .LBB0_675
	s_mul_hi_i32 s4, s16, 0x2e8ba2e9
	s_lshr_b32 s5, s4, 31
	s_ashr_i32 s4, s4, 5
	s_add_i32 s5, s4, s5
	s_mul_i32 s4, s5, 0xb0
	s_sub_i32 s6, s16, s4
	s_lshl_b32 s4, s6, 6
	s_cmpk_gt_i32 s6, 0x57
	s_cselect_b32 s6, 0xffffea00, 0
	s_cselect_b32 s10, 0x80, 0
	s_add_i32 s6, s6, s4
	s_lshl_b32 s6, s6, 1
	s_and_b32 s11, s4, 64
	s_and_b32 s6, s6, 0xffffff00
	s_or_b32 s10, s11, s10
	s_or_b32 s17, s10, s6
	s_lshl_b32 s6, s5, 6
	v_or_b32_e32 v5, s6, v139
	v_mov_b64_e32 v[66:67], s[0:1]
	v_mad_i64_i32 v[6:7], s[10:11], v5, s28, v[66:67]
	s_ashr_i32 s5, s4, 31
	v_or_b32_e32 v10, 4, v5
	v_or_b32_e32 v14, 8, v5
	v_or_b32_e32 v18, 12, v5
	v_or_b32_e32 v22, 16, v5
	v_or_b32_e32 v26, 20, v5
	v_or_b32_e32 v30, 24, v5
	v_or_b32_e32 v34, 28, v5
	v_or_b32_e32 v38, 32, v5
	v_or_b32_e32 v42, 36, v5
	v_or_b32_e32 v46, 40, v5
	v_or_b32_e32 v50, 44, v5
	v_or_b32_e32 v54, 48, v5
	v_or_b32_e32 v58, 52, v5
	v_or_b32_e32 v62, 56, v5
	v_or_b32_e32 v5, 60, v5
	s_lshl_b64 s[10:11], s[4:5], 2
	v_lshlrev_b32_e32 v2, 4, v4
	v_mad_i64_i32 v[10:11], s[12:13], v10, s28, v[66:67]
	v_mad_i64_i32 v[14:15], s[12:13], v14, s28, v[66:67]
	v_mad_i64_i32 v[18:19], s[12:13], v18, s28, v[66:67]
	v_mad_i64_i32 v[22:23], s[12:13], v22, s28, v[66:67]
	v_mad_i64_i32 v[26:27], s[12:13], v26, s28, v[66:67]
	v_mad_i64_i32 v[30:31], s[12:13], v30, s28, v[66:67]
	v_mad_i64_i32 v[34:35], s[12:13], v34, s28, v[66:67]
	v_mad_i64_i32 v[38:39], s[12:13], v38, s28, v[66:67]
	v_mad_i64_i32 v[42:43], s[12:13], v42, s28, v[66:67]
	v_mad_i64_i32 v[46:47], s[12:13], v46, s28, v[66:67]
	v_mad_i64_i32 v[50:51], s[12:13], v50, s28, v[66:67]
	v_mad_i64_i32 v[54:55], s[12:13], v54, s28, v[66:67]
	v_mad_i64_i32 v[58:59], s[12:13], v58, s28, v[66:67]
	v_mad_i64_i32 v[62:63], s[12:13], v62, s28, v[66:67]
	v_mad_i64_i32 v[66:67], s[12:13], v5, s28, v[66:67]
	v_lshl_add_u64 v[6:7], v[6:7], 0, s[10:11]
	v_and_b32_e32 v2, 0xf0, v2
	v_lshl_add_u64 v[10:11], v[10:11], 0, s[10:11]
	v_lshl_add_u64 v[14:15], v[14:15], 0, s[10:11]
	v_lshl_add_u64 v[18:19], v[18:19], 0, s[10:11]
	v_lshl_add_u64 v[22:23], v[22:23], 0, s[10:11]
	v_lshl_add_u64 v[26:27], v[26:27], 0, s[10:11]
	v_lshl_add_u64 v[30:31], v[30:31], 0, s[10:11]
	v_lshl_add_u64 v[34:35], v[34:35], 0, s[10:11]
	v_lshl_add_u64 v[38:39], v[38:39], 0, s[10:11]
	v_lshl_add_u64 v[42:43], v[42:43], 0, s[10:11]
	v_lshl_add_u64 v[46:47], v[46:47], 0, s[10:11]
	v_lshl_add_u64 v[50:51], v[50:51], 0, s[10:11]
	v_lshl_add_u64 v[54:55], v[54:55], 0, s[10:11]
	v_lshl_add_u64 v[58:59], v[58:59], 0, s[10:11]
	v_lshl_add_u64 v[62:63], v[62:63], 0, s[10:11]
	v_lshl_add_u64 v[66:67], v[66:67], 0, s[10:11]
	v_lshl_add_u64 v[6:7], v[6:7], 0, v[2:3]
	v_lshl_add_u64 v[10:11], v[10:11], 0, v[2:3]
	v_lshl_add_u64 v[14:15], v[14:15], 0, v[2:3]
	v_lshl_add_u64 v[18:19], v[18:19], 0, v[2:3]
	v_lshl_add_u64 v[22:23], v[22:23], 0, v[2:3]
	v_lshl_add_u64 v[26:27], v[26:27], 0, v[2:3]
	v_lshl_add_u64 v[30:31], v[30:31], 0, v[2:3]
	v_lshl_add_u64 v[34:35], v[34:35], 0, v[2:3]
	v_lshl_add_u64 v[38:39], v[38:39], 0, v[2:3]
	v_lshl_add_u64 v[42:43], v[42:43], 0, v[2:3]
	v_lshl_add_u64 v[46:47], v[46:47], 0, v[2:3]
	v_lshl_add_u64 v[50:51], v[50:51], 0, v[2:3]
	v_lshl_add_u64 v[54:55], v[54:55], 0, v[2:3]
	v_lshl_add_u64 v[58:59], v[58:59], 0, v[2:3]
	v_lshl_add_u64 v[62:63], v[62:63], 0, v[2:3]
	v_lshl_add_u64 v[66:67], v[66:67], 0, v[2:3]
	global_load_dwordx4 v[6:9], v[6:7], off nt
	s_nop 0
	global_load_dwordx4 v[10:13], v[10:11], off nt
	s_nop 0
	global_load_dwordx4 v[14:17], v[14:15], off nt
	s_nop 0
	global_load_dwordx4 v[18:21], v[18:19], off nt
	s_nop 0
	global_load_dwordx4 v[22:25], v[22:23], off nt
	s_nop 0
	global_load_dwordx4 v[26:29], v[26:27], off nt
	s_nop 0
	global_load_dwordx4 v[30:33], v[30:31], off nt
	s_nop 0
	global_load_dwordx4 v[34:37], v[34:35], off nt
	s_nop 0
	global_load_dwordx4 v[38:41], v[38:39], off nt
	s_nop 0
	global_load_dwordx4 v[42:45], v[42:43], off nt
	s_nop 0
	global_load_dwordx4 v[46:49], v[46:47], off nt
	s_nop 0
	global_load_dwordx4 v[50:53], v[50:51], off nt
	s_nop 0
	global_load_dwordx4 v[54:57], v[54:55], off nt
	s_nop 0
	global_load_dwordx4 v[58:61], v[58:59], off nt
	s_nop 0
	global_load_dwordx4 v[62:65], v[62:63], off nt
	s_nop 0
	global_load_dwordx4 v[66:69], v[66:67], off nt

; __device__ __forceinline__ void tr_load(const TrItem& t, f32x4 (&v)[16], int lane) {
;     const int c4 = 4 * (lane & 15), kq = lane >> 4; const bool okc = t.n0 + c4 < t.N;
; #pragma unroll
;     for (int i = 0; i < 16; ++i) { v[i] = (f32x4){0.f, 0.f, 0.f, 0.f}; if (okc) v[i] = *(const f32x4*)(t.W + (size_t)(t.k0 + 4 * i + kq) * t.N + t.n0 + c4); }
; }
;     ...
;     for (; it < it1; it += NGW) {
;         const bool more = it + NGW < it1;
;         if (more) { TR_DESCRIBE(it + NGW, tn); tr_load(tn, vn, lane); }
.LBB0_678:
	s_waitcnt vmcnt(0)
	v_readlane_b32 s7, v253, 5
	s_add_i32 s16, s16, s7
	s_cmpk_lt_i32 s16, 0x1600
	s_cselect_b64 s[12:13], -1, 0
	s_cmpk_gt_i32 s16, 0x15ff
	s_cselect_b64 s[10:11], -1, 0
	s_and_b64 vcc, exec, s[10:11]
	s_cbranch_vccnz .LBB0_696
	s_mul_hi_i32 s7, s16, 0x2e8ba2e9
	s_lshr_b32 s8, s7, 31
	s_ashr_i32 s20, s7, 5
	s_add_i32 s20, s20, s8
	s_mul_i32 s7, s20, 0xffffd400
	s_add_i32 s8, s5, s7
	v_mov_b32_e32 v72, v3
	v_mov_b32_e32 v73, v3
	v_add_u32_e32 v2, s8, v138
	v_mov_b32_e32 v70, v3
	v_mov_b32_e32 v71, v3
	v_mov_b64_e32 v[76:77], v[72:73]
	v_mov_b64_e32 v[80:81], v[72:73]
	s_lshl_b32 s19, s20, 6
	v_cmp_gt_i32_e32 vcc, s25, v2
	v_lshlrev_b32_e32 v134, 2, v138
	v_mov_b64_e32 v[74:75], v[70:71]
	v_mov_b64_e32 v[78:79], v[70:71]
	s_and_saveexec_b64 s[14:15], vcc
	s_cbranch_execz .LBB0_681
	v_or_b32_e32 v2, s19, v139
	v_mov_b64_e32 v[4:5], s[0:1]
	v_mad_i64_i32 v[74:75], s[22:23], v2, s28, v[4:5]
	s_ashr_i32 s9, s8, 31
	s_lshl_b64 s[22:23], s[8:9], 2
	v_or_b32_e32 v2, 4, v2
	v_lshl_add_u64 v[74:75], v[74:75], 0, s[22:23]
	v_mov_b32_e32 v135, v3
	v_mad_i64_i32 v[4:5], s[26:27], v2, s28, v[4:5]
	v_lshl_add_u64 v[74:75], v[74:75], 0, v[134:135]
	v_lshl_add_u64 v[4:5], v[4:5], 0, s[22:23]
	v_lshl_add_u64 v[4:5], v[4:5], 0, v[134:135]
	global_load_dwordx4 v[78:81], v[74:75], off nt
	s_nop 0
	global_load_dwordx4 v[74:77], v[4:5], off nt
.LBB0_681:
	s_or_b64 exec, exec, s[14:15]
	v_mov_b64_e32 v[84:85], v[72:73]
	v_or_b32_e32 v136, s19, v139
	v_mov_b64_e32 v[82:83], v[70:71]
	s_and_saveexec_b64 s[14:15], vcc
	s_cbranch_execz .LBB0_683
	v_or_b32_e32 v2, 8, v136
	v_mov_b64_e32 v[4:5], s[0:1]
	v_mad_i64_i32 v[70:71], s[22:23], v2, s28, v[4:5]
	s_ashr_i32 s9, s8, 31
	s_lshl_b64 s[22:23], s[8:9], 2
	v_or_b32_e32 v2, 12, v136
	v_lshl_add_u64 v[70:71], v[70:71], 0, s[22:23]
	v_mov_b32_e32 v135, v3
	v_mad_i64_i32 v[4:5], s[26:27], v2, s28, v[4:5]
	v_lshl_add_u64 v[70:71], v[70:71], 0, v[134:135]
	v_lshl_add_u64 v[4:5], v[4:5], 0, s[22:23]
	v_lshl_add_u64 v[4:5], v[4:5], 0, v[134:135]
	global_load_dwordx4 v[82:85], v[70:71], off nt
	s_nop 0
	global_load_dwordx4 v[70:73], v[4:5], off nt
.LBB0_683:
	s_or_b64 exec, exec, s[14:15]
	v_mov_b32_e32 v4, v3
	v_mov_b32_e32 v5, v3
	v_mov_b32_e32 v2, v3
	v_mov_b64_e32 v[88:89], v[4:5]
	v_mov_b64_e32 v[92:93], v[4:5]
	v_mov_b64_e32 v[86:87], v[2:3]
	v_mov_b64_e32 v[90:91], v[2:3]
	s_and_saveexec_b64 s[14:15], vcc
	s_cbranch_execz .LBB0_685
	v_or_b32_e32 v88, 16, v136
	v_mov_b64_e32 v[86:87], s[0:1]
	v_mad_i64_i32 v[88:89], s[22:23], v88, s28, v[86:87]
	s_ashr_i32 s9, s8, 31
	v_or_b32_e32 v90, 20, v136
	s_lshl_b64 s[22:23], s[8:9], 2
	v_mad_i64_i32 v[86:87], s[26:27], v90, s28, v[86:87]
	v_lshl_add_u64 v[88:89], v[88:89], 0, s[22:23]
	v_mov_b32_e32 v135, v3
	v_lshl_add_u64 v[86:87], v[86:87], 0, s[22:23]
	v_lshl_add_u64 v[88:89], v[88:89], 0, v[134:135]
	v_lshl_add_u64 v[86:87], v[86:87], 0, v[134:135]
	global_load_dwordx4 v[90:93], v[88:89], off nt
	s_nop 0
	global_load_dwordx4 v[86:89], v[86:87], off nt
.LBB0_685:
	s_or_b64 exec, exec, s[14:15]
	v_mov_b64_e32 v[96:97], v[4:5]
	v_mov_b64_e32 v[100:101], v[4:5]
	v_mov_b64_e32 v[94:95], v[2:3]
	v_mov_b64_e32 v[98:99], v[2:3]
	s_and_saveexec_b64 s[14:15], vcc
	s_cbranch_execz .LBB0_687
	v_or_b32_e32 v2, 24, v136
	v_mov_b64_e32 v[4:5], s[0:1]
	v_mad_i64_i32 v[94:95], s[22:23], v2, s28, v[4:5]
	s_ashr_i32 s9, s8, 31
	s_lshl_b64 s[22:23], s[8:9], 2
	v_or_b32_e32 v2, 28, v136
	v_lshl_add_u64 v[94:95], v[94:95], 0, s[22:23]
	v_mov_b32_e32 v135, v3
	v_mad_i64_i32 v[4:5], s[26:27], v2, s28, v[4:5]
	v_lshl_add_u64 v[94:95], v[94:95], 0, v[134:135]
	v_lshl_add_u64 v[4:5], v[4:5], 0, s[22:23]
	v_lshl_add_u64 v[4:5], v[4:5], 0, v[134:135]
	global_load_dwordx4 v[98:101], v[94:95], off nt
	s_nop 0
	global_load_dwordx4 v[94:97], v[4:5], off nt
; __device__ __forceinline__ void tr_load(const TrItem& t, f32x4 (&v)[16], int lane) {
;     const int c4 = 4 * (lane & 15), kq = lane >> 4; const bool okc = t.n0 + c4 < t.N;
; #pragma unroll
;     for (int i = 0; i < 16; ++i) { v[i] = (f32x4){0.f, 0.f, 0.f, 0.f}; if (okc) v[i] = *(const f32x4*)(t.W + (size_t)(t.k0 + 4 * i + kq) * t.N + t.n0 + c4); }
; }
.LBB0_687:
	s_or_b64 exec, exec, s[14:15]
	v_mov_b32_e32 v4, v3
	v_mov_b32_e32 v5, v3
	v_mov_b32_e32 v2, v3
	v_mov_b64_e32 v[104:105], v[4:5]
	v_mov_b64_e32 v[108:109], v[4:5]
	v_mov_b64_e32 v[102:103], v[2:3]
	v_mov_b64_e32 v[106:107], v[2:3]
	s_and_saveexec_b64 s[14:15], vcc
	s_cbranch_execz .LBB0_689
	v_or_b32_e32 v104, 32, v136
	v_mov_b64_e32 v[102:103], s[0:1]
	v_mad_i64_i32 v[104:105], s[22:23], v104, s28, v[102:103]
	s_ashr_i32 s9, s8, 31
	v_or_b32_e32 v106, 36, v136
	s_lshl_b64 s[22:23], s[8:9], 2
	v_mad_i64_i32 v[102:103], s[26:27], v106, s28, v[102:103]
	v_lshl_add_u64 v[104:105], v[104:105], 0, s[22:23]
	v_mov_b32_e32 v135, v3
	v_lshl_add_u64 v[102:103], v[102:103], 0, s[22:23]
	v_lshl_add_u64 v[104:105], v[104:105], 0, v[134:135]
	v_lshl_add_u64 v[102:103], v[102:103], 0, v[134:135]
	global_load_dwordx4 v[106:109], v[104:105], off nt
	s_nop 0
	global_load_dwordx4 v[102:105], v[102:103], off nt
.LBB0_689:
	s_or_b64 exec, exec, s[14:15]
	v_mov_b64_e32 v[112:113], v[4:5]
	v_mov_b64_e32 v[116:117], v[4:5]
	v_mov_b64_e32 v[110:111], v[2:3]
	v_mov_b64_e32 v[114:115], v[2:3]
	s_and_saveexec_b64 s[14:15], vcc
	s_cbranch_execz .LBB0_691
	v_or_b32_e32 v2, 40, v136
	v_mov_b64_e32 v[4:5], s[0:1]
	v_mad_i64_i32 v[110:111], s[22:23], v2, s28, v[4:5]
	s_ashr_i32 s9, s8, 31
	s_lshl_b64 s[22:23], s[8:9], 2
	v_or_b32_e32 v2, 44, v136
	v_lshl_add_u64 v[110:111], v[110:111], 0, s[22:23]
	v_mov_b32_e32 v135, v3
	v_mad_i64_i32 v[4:5], s[26:27], v2, s28, v[4:5]
	v_lshl_add_u64 v[110:111], v[110:111], 0, v[134:135]
	v_lshl_add_u64 v[4:5], v[4:5], 0, s[22:23]
	v_lshl_add_u64 v[4:5], v[4:5], 0, v[134:135]
	global_load_dwordx4 v[114:117], v[110:111], off nt
	s_nop 0
	global_load_dwordx4 v[110:113], v[4:5], off nt
.LBB0_691:
	s_or_b64 exec, exec, s[14:15]
	v_mov_b32_e32 v4, v3
	v_mov_b32_e32 v5, v3
	v_mov_b32_e32 v2, v3
	v_mov_b64_e32 v[120:121], v[4:5]
	v_mov_b64_e32 v[124:125], v[4:5]
	v_mov_b64_e32 v[118:119], v[2:3]
	v_mov_b64_e32 v[122:123], v[2:3]
	s_and_saveexec_b64 s[14:15], vcc
	s_cbranch_execz .LBB0_693
	v_or_b32_e32 v120, 48, v136
	v_mov_b64_e32 v[118:119], s[0:1]
	v_mad_i64_i32 v[120:121], s[22:23], v120, s28, v[118:119]
	s_ashr_i32 s9, s8, 31
	v_or_b32_e32 v122, 52, v136
	s_lshl_b64 s[22:23], s[8:9], 2
	v_mad_i64_i32 v[118:119], s[26:27], v122, s28, v[118:119]
	v_lshl_add_u64 v[120:121], v[120:121], 0, s[22:23]
	v_mov_b32_e32 v135, v3
	v_lshl_add_u64 v[118:119], v[118:119], 0, s[22:23]
	v_lshl_add_u64 v[120:121], v[120:121], 0, v[134:135]
	v_lshl_add_u64 v[118:119], v[118:119], 0, v[134:135]
	global_load_dwordx4 v[122:125], v[120:121], off nt
	s_nop 0
	global_load_dwordx4 v[118:121], v[118:119], off nt
.LBB0_693:
	s_or_b64 exec, exec, s[14:15]
	s_mulk_i32 s20, 0xff50
	s_add_i32 s9, s16, s20
	s_cmpk_gt_i32 s9, 0x57
	v_mov_b64_e32 v[128:129], v[4:5]
	v_mov_b64_e32 v[132:133], v[4:5]
	s_cselect_b32 s21, 0xffffea00, 0
	s_cselect_b32 s20, 0x80, 0
	v_mov_b64_e32 v[126:127], v[2:3]
	v_mov_b64_e32 v[130:131], v[2:3]
	s_and_saveexec_b64 s[14:15], vcc
	s_cbranch_execz .LBB0_695
	v_or_b32_e32 v2, 56, v136
	v_mov_b64_e32 v[4:5], s[0:1]
	v_mad_i64_i32 v[126:127], s[22:23], v2, s28, v[4:5]
	s_ashr_i32 s9, s8, 31
	s_lshl_b64 s[22:23], s[8:9], 2
	v_or_b32_e32 v2, 60, v136
	v_lshl_add_u64 v[126:127], v[126:127], 0, s[22:23]
	v_mov_b32_e32 v135, v3
	v_mad_i64_i32 v[4:5], s[26:27], v2, s28, v[4:5]
	v_lshl_add_u64 v[126:127], v[126:127], 0, v[134:135]
	v_lshl_add_u64 v[4:5], v[4:5], 0, s[22:23]
	v_lshl_add_u64 v[4:5], v[4:5], 0, v[134:135]
	global_load_dwordx4 v[126:129], v[126:127], off nt
	s_nop 0
	global_load_dwordx4 v[130:133], v[4:5], off nt

; __device__ __forceinline__ void tr_load(const TrItem& t, f32x4 (&v)[16], int lane) {
;     const int c4 = 4 * (lane & 15), kq = lane >> 4; const bool okc = t.n0 + c4 < t.N;
; #pragma unroll
;     for (int i = 0; i < 16; ++i) { v[i] = (f32x4){0.f, 0.f, 0.f, 0.f}; if (okc) v[i] = *(const f32x4*)(t.W + (size_t)(t.k0 + 4 * i + kq) * t.N + t.n0 + c4); }
; }
;     ...
;     int it = it0 + gw;
;     if (it < it1) { TR_DESCRIBE(it, tc); tr_load(tc, vc, lane); }
.LBB0_1448:
	v_lshlrev_b32_e32 v2, 2, v72
	v_and_b32_e32 v6, 60, v2
	v_lshrrev_b32_e32 v7, 4, v72
	v_or_b32_e32 v2, s10, v6
	v_mov_b32_e32 v4, v3
	v_mov_b32_e32 v5, v3
	v_cmp_gt_i32_e32 vcc, s30, v2
	v_mov_b32_e32 v2, v3
	v_add_u32_e32 v73, s8, v7
	v_lshlrev_b32_e32 v70, 2, v6
	v_mov_b64_e32 v[12:13], v[4:5]
	v_mov_b64_e32 v[8:9], v[4:5]
	v_mov_b64_e32 v[10:11], v[2:3]
	v_mov_b64_e32 v[6:7], v[2:3]
	s_and_saveexec_b64 s[18:19], vcc
	s_cbranch_execz .LBB0_1450
	v_add_u32_e32 v8, 4, v73
	v_mad_i64_i32 v[6:7], s[20:21], s30, v73, 0
	s_ashr_i32 s11, s10, 31
	v_mad_i64_i32 v[8:9], s[22:23], s30, v8, 0
	v_lshl_add_u64 v[6:7], v[6:7], 2, s[16:17]
	s_lshl_b64 s[20:21], s[10:11], 2
	v_lshl_add_u64 v[8:9], v[8:9], 2, s[16:17]
	v_lshl_add_u64 v[6:7], v[6:7], 0, s[20:21]
	v_mov_b32_e32 v71, v3
	v_lshl_add_u64 v[8:9], v[8:9], 0, s[20:21]
	v_lshl_add_u64 v[6:7], v[6:7], 0, v[70:71]
	v_lshl_add_u64 v[10:11], v[8:9], 0, v[70:71]
	global_load_dwordx4 v[6:9], v[6:7], off nt
	s_nop 0
	global_load_dwordx4 v[10:13], v[10:11], off nt
.LBB0_1450:
	s_or_b64 exec, exec, s[18:19]
	v_mov_b64_e32 v[20:21], v[4:5]
	v_mov_b64_e32 v[16:17], v[4:5]
	v_mov_b64_e32 v[18:19], v[2:3]
	v_mov_b64_e32 v[14:15], v[2:3]
	s_and_saveexec_b64 s[18:19], vcc
	s_cbranch_execz .LBB0_1452
	v_add_u32_e32 v2, 8, v73
	v_mad_i64_i32 v[4:5], s[20:21], s30, v2, 0
	v_add_u32_e32 v2, 12, v73
	s_ashr_i32 s11, s10, 31
	v_mad_i64_i32 v[14:15], s[22:23], s30, v2, 0
	v_lshl_add_u64 v[4:5], v[4:5], 2, s[16:17]
	s_lshl_b64 s[20:21], s[10:11], 2
	v_lshl_add_u64 v[14:15], v[14:15], 2, s[16:17]
	v_lshl_add_u64 v[4:5], v[4:5], 0, s[20:21]
	v_mov_b32_e32 v71, v3
	v_lshl_add_u64 v[14:15], v[14:15], 0, s[20:21]
	v_lshl_add_u64 v[4:5], v[4:5], 0, v[70:71]
	v_lshl_add_u64 v[18:19], v[14:15], 0, v[70:71]
	global_load_dwordx4 v[14:17], v[4:5], off nt
	s_nop 0
	global_load_dwordx4 v[18:21], v[18:19], off nt
.LBB0_1452:
	s_or_b64 exec, exec, s[18:19]
	v_mov_b32_e32 v4, v3
	v_mov_b32_e32 v5, v3
	v_mov_b32_e32 v2, v3
	v_mov_b64_e32 v[28:29], v[4:5]
	v_mov_b64_e32 v[24:25], v[4:5]
	v_mov_b64_e32 v[26:27], v[2:3]
	v_mov_b64_e32 v[22:23], v[2:3]
	s_and_saveexec_b64 s[18:19], vcc
	s_cbranch_execz .LBB0_1454
	v_add_u32_e32 v22, 16, v73
	v_add_u32_e32 v24, 20, v73
	v_mad_i64_i32 v[22:23], s[20:21], s30, v22, 0
	s_ashr_i32 s11, s10, 31
	v_mad_i64_i32 v[24:25], s[22:23], s30, v24, 0
	v_lshl_add_u64 v[22:23], v[22:23], 2, s[16:17]
	s_lshl_b64 s[20:21], s[10:11], 2
	v_lshl_add_u64 v[24:25], v[24:25], 2, s[16:17]
	v_lshl_add_u64 v[22:23], v[22:23], 0, s[20:21]
	v_mov_b32_e32 v71, v3
	v_lshl_add_u64 v[24:25], v[24:25], 0, s[20:21]
	v_lshl_add_u64 v[22:23], v[22:23], 0, v[70:71]
	v_lshl_add_u64 v[26:27], v[24:25], 0, v[70:71]
	global_load_dwordx4 v[22:25], v[22:23], off nt
	s_nop 0
	global_load_dwordx4 v[26:29], v[26:27], off nt
.LBB0_1454:
	s_or_b64 exec, exec, s[18:19]
	v_mov_b64_e32 v[36:37], v[4:5]
	v_mov_b64_e32 v[32:33], v[4:5]
	v_mov_b64_e32 v[34:35], v[2:3]
	v_mov_b64_e32 v[30:31], v[2:3]
	s_and_saveexec_b64 s[18:19], vcc
	s_cbranch_execz .LBB0_1456
	v_add_u32_e32 v2, 24, v73
	v_mad_i64_i32 v[4:5], s[20:21], s30, v2, 0
	v_add_u32_e32 v2, 28, v73
	s_ashr_i32 s11, s10, 31
	v_mad_i64_i32 v[30:31], s[22:23], s30, v2, 0
	v_lshl_add_u64 v[4:5], v[4:5], 2, s[16:17]
	s_lshl_b64 s[20:21], s[10:11], 2
	v_lshl_add_u64 v[30:31], v[30:31], 2, s[16:17]
	v_lshl_add_u64 v[4:5], v[4:5], 0, s[20:21]
	v_mov_b32_e32 v71, v3
	v_lshl_add_u64 v[30:31], v[30:31], 0, s[20:21]
	v_lshl_add_u64 v[4:5], v[4:5], 0, v[70:71]
	v_lshl_add_u64 v[34:35], v[30:31], 0, v[70:71]
	global_load_dwordx4 v[30:33], v[4:5], off nt
	s_nop 0
	global_load_dwordx4 v[34:37], v[34:35], off nt
; __device__ __forceinline__ void tr_load(const TrItem& t, f32x4 (&v)[16], int lane) {
;     const int c4 = 4 * (lane & 15), kq = lane >> 4; const bool okc = t.n0 + c4 < t.N;
; #pragma unroll
;     for (int i = 0; i < 16; ++i) { v[i] = (f32x4){0.f, 0.f, 0.f, 0.f}; if (okc) v[i] = *(const f32x4*)(t.W + (size_t)(t.k0 + 4 * i + kq) * t.N + t.n0 + c4); }
; }
.LBB0_1456:
	s_or_b64 exec, exec, s[18:19]
	v_mov_b32_e32 v4, v3
	v_mov_b32_e32 v5, v3
	v_mov_b32_e32 v2, v3
	v_mov_b64_e32 v[44:45], v[4:5]
	v_mov_b64_e32 v[40:41], v[4:5]
	v_mov_b64_e32 v[42:43], v[2:3]
	v_mov_b64_e32 v[38:39], v[2:3]
	s_and_saveexec_b64 s[18:19], vcc
	s_cbranch_execz .LBB0_1458
	v_add_u32_e32 v38, 32, v73
	v_add_u32_e32 v40, 36, v73
	v_mad_i64_i32 v[38:39], s[20:21], s30, v38, 0
	s_ashr_i32 s11, s10, 31
	v_mad_i64_i32 v[40:41], s[22:23], s30, v40, 0
	v_lshl_add_u64 v[38:39], v[38:39], 2, s[16:17]
	s_lshl_b64 s[20:21], s[10:11], 2
	v_lshl_add_u64 v[40:41], v[40:41], 2, s[16:17]
	v_lshl_add_u64 v[38:39], v[38:39], 0, s[20:21]
	v_mov_b32_e32 v71, v3
	v_lshl_add_u64 v[40:41], v[40:41], 0, s[20:21]
	v_lshl_add_u64 v[38:39], v[38:39], 0, v[70:71]
	v_lshl_add_u64 v[42:43], v[40:41], 0, v[70:71]
	global_load_dwordx4 v[38:41], v[38:39], off nt
	s_nop 0
	global_load_dwordx4 v[42:45], v[42:43], off nt
.LBB0_1458:
	s_or_b64 exec, exec, s[18:19]
	v_mov_b64_e32 v[52:53], v[4:5]
	v_mov_b64_e32 v[48:49], v[4:5]
	v_mov_b64_e32 v[50:51], v[2:3]
	v_mov_b64_e32 v[46:47], v[2:3]
	s_and_saveexec_b64 s[18:19], vcc
	s_cbranch_execz .LBB0_1460
	v_add_u32_e32 v2, 40, v73
	v_mad_i64_i32 v[4:5], s[20:21], s30, v2, 0
	v_add_u32_e32 v2, 44, v73
	s_ashr_i32 s11, s10, 31
	v_mad_i64_i32 v[46:47], s[22:23], s30, v2, 0
	v_lshl_add_u64 v[4:5], v[4:5], 2, s[16:17]
	s_lshl_b64 s[20:21], s[10:11], 2
	v_lshl_add_u64 v[46:47], v[46:47], 2, s[16:17]
	v_lshl_add_u64 v[4:5], v[4:5], 0, s[20:21]
	v_mov_b32_e32 v71, v3
	v_lshl_add_u64 v[46:47], v[46:47], 0, s[20:21]
	v_lshl_add_u64 v[4:5], v[4:5], 0, v[70:71]
	v_lshl_add_u64 v[50:51], v[46:47], 0, v[70:71]
	global_load_dwordx4 v[46:49], v[4:5], off nt
	s_nop 0
	global_load_dwordx4 v[50:53], v[50:51], off nt
.LBB0_1460:
	s_or_b64 exec, exec, s[18:19]
	v_mov_b32_e32 v4, v3
	v_mov_b32_e32 v5, v3
	v_mov_b32_e32 v2, v3
	v_mov_b64_e32 v[60:61], v[4:5]
	v_mov_b64_e32 v[56:57], v[4:5]
	v_mov_b64_e32 v[58:59], v[2:3]
	v_mov_b64_e32 v[54:55], v[2:3]
	s_and_saveexec_b64 s[18:19], vcc
	s_cbranch_execz .LBB0_1462
	v_add_u32_e32 v54, 48, v73
	v_add_u32_e32 v56, 52, v73
	v_mad_i64_i32 v[54:55], s[20:21], s30, v54, 0
	s_ashr_i32 s11, s10, 31
	v_mad_i64_i32 v[56:57], s[22:23], s30, v56, 0
	v_lshl_add_u64 v[54:55], v[54:55], 2, s[16:17]
	s_lshl_b64 s[20:21], s[10:11], 2
	v_lshl_add_u64 v[56:57], v[56:57], 2, s[16:17]
	v_lshl_add_u64 v[54:55], v[54:55], 0, s[20:21]
	v_mov_b32_e32 v71, v3
	v_lshl_add_u64 v[56:57], v[56:57], 0, s[20:21]
	v_lshl_add_u64 v[54:55], v[54:55], 0, v[70:71]
	v_lshl_add_u64 v[58:59], v[56:57], 0, v[70:71]
	global_load_dwordx4 v[54:57], v[54:55], off nt
	s_nop 0
	global_load_dwordx4 v[58:61], v[58:59], off nt
.LBB0_1462:
	s_or_b64 exec, exec, s[18:19]
	v_mov_b64_e32 v[64:65], v[4:5]
	v_mov_b64_e32 v[68:69], v[4:5]
	v_mov_b64_e32 v[62:63], v[2:3]
	v_mov_b64_e32 v[66:67], v[2:3]
	s_and_saveexec_b64 s[18:19], vcc
	s_cbranch_execz .LBB0_1464
	v_add_u32_e32 v2, 56, v73
	v_mad_i64_i32 v[4:5], s[20:21], s30, v2, 0
	v_add_u32_e32 v2, 60, v73
	s_ashr_i32 s11, s10, 31
	v_mad_i64_i32 v[62:63], s[22:23], s30, v2, 0
	v_lshl_add_u64 v[4:5], v[4:5], 2, s[16:17]
	s_lshl_b64 s[20:21], s[10:11], 2
	v_lshl_add_u64 v[62:63], v[62:63], 2, s[16:17]
	v_lshl_add_u64 v[4:5], v[4:5], 0, s[20:21]
	v_mov_b32_e32 v71, v3
	v_lshl_add_u64 v[62:63], v[62:63], 0, s[20:21]
	v_lshl_add_u64 v[4:5], v[4:5], 0, v[70:71]
	v_lshl_add_u64 v[66:67], v[62:63], 0, v[70:71]
	global_load_dwordx4 v[62:65], v[4:5], off nt
	s_nop 0
	global_load_dwordx4 v[66:69], v[66:67], off nt

; __device__ __forceinline__ void tr_load(const TrItem& t, f32x4 (&v)[16], int lane) {
;     const int c4 = 4 * (lane & 15), kq = lane >> 4; const bool okc = t.n0 + c4 < t.N;
; #pragma unroll
;     for (int i = 0; i < 16; ++i) { v[i] = (f32x4){0.f, 0.f, 0.f, 0.f}; if (okc) v[i] = *(const f32x4*)(t.W + (size_t)(t.k0 + 4 * i + kq) * t.N + t.n0 + c4); }
; }
;     ...
;     for (; it < it1; it += NGW) {
;         const bool more = it + NGW < it1;
;         if (more) { TR_DESCRIBE(it + NGW, tn); tr_load(tn, vn, lane); }
.LBB0_1474:
	v_or_b32_e32 v2, s14, v138
	v_mov_b32_e32 v4, v3
	v_mov_b32_e32 v5, v3
	v_cmp_gt_i32_e32 vcc, s37, v2
	v_mov_b32_e32 v2, v3
	v_mov_b64_e32 v[72:73], v[4:5]
	v_mov_b64_e32 v[76:77], v[4:5]
	v_lshlrev_b32_e32 v134, 2, v138
	v_mov_b64_e32 v[70:71], v[2:3]
	v_mov_b64_e32 v[74:75], v[2:3]
	s_and_saveexec_b64 s[24:25], vcc
	s_cbranch_execz .LBB0_1476
	v_add_u32_e32 v70, s35, v139
	v_add_u32_e32 v72, s35, v141
	v_mad_i64_i32 v[70:71], s[40:41], s37, v70, 0
	s_ashr_i32 s15, s14, 31
	v_mad_i64_i32 v[72:73], s[42:43], s37, v72, 0
	v_lshl_add_u64 v[70:71], v[70:71], 2, s[22:23]
	s_lshl_b64 s[40:41], s[14:15], 2
	v_lshl_add_u64 v[72:73], v[72:73], 2, s[22:23]
	v_lshl_add_u64 v[70:71], v[70:71], 0, s[40:41]
	v_mov_b32_e32 v135, v3
	v_lshl_add_u64 v[72:73], v[72:73], 0, s[40:41]
	v_lshl_add_u64 v[70:71], v[70:71], 0, v[134:135]
	v_lshl_add_u64 v[72:73], v[72:73], 0, v[134:135]
	global_load_dwordx4 v[74:77], v[70:71], off nt
	s_nop 0
	global_load_dwordx4 v[70:73], v[72:73], off nt
.LBB0_1476:
	s_or_b64 exec, exec, s[24:25]
	v_mov_b64_e32 v[80:81], v[4:5]
	v_mov_b64_e32 v[84:85], v[4:5]
	v_mov_b64_e32 v[78:79], v[2:3]
	v_mov_b64_e32 v[82:83], v[2:3]
	s_and_saveexec_b64 s[24:25], vcc
	s_cbranch_execz .LBB0_1478
	v_add_u32_e32 v2, s35, v142
	v_mad_i64_i32 v[4:5], s[40:41], s37, v2, 0
	v_add_u32_e32 v2, s35, v143
	s_ashr_i32 s15, s14, 31
	v_mad_i64_i32 v[78:79], s[42:43], s37, v2, 0
	v_lshl_add_u64 v[4:5], v[4:5], 2, s[22:23]
	s_lshl_b64 s[40:41], s[14:15], 2
	v_lshl_add_u64 v[78:79], v[78:79], 2, s[22:23]
	v_lshl_add_u64 v[4:5], v[4:5], 0, s[40:41]
	v_mov_b32_e32 v135, v3
	v_lshl_add_u64 v[78:79], v[78:79], 0, s[40:41]
	v_lshl_add_u64 v[4:5], v[4:5], 0, v[134:135]
	v_lshl_add_u64 v[78:79], v[78:79], 0, v[134:135]
	global_load_dwordx4 v[82:85], v[4:5], off nt
	s_nop 0
	global_load_dwordx4 v[78:81], v[78:79], off nt
.LBB0_1478:
	s_or_b64 exec, exec, s[24:25]
	v_mov_b32_e32 v4, v3
	v_mov_b32_e32 v5, v3
	v_mov_b32_e32 v2, v3
	v_mov_b64_e32 v[88:89], v[4:5]
	v_mov_b64_e32 v[92:93], v[4:5]
	v_mov_b64_e32 v[86:87], v[2:3]
	v_mov_b64_e32 v[90:91], v[2:3]
	s_and_saveexec_b64 s[24:25], vcc
	s_cbranch_execz .LBB0_1480
	v_add_u32_e32 v86, s35, v144
	v_add_u32_e32 v88, s35, v145
	v_mad_i64_i32 v[86:87], s[40:41], s37, v86, 0
	s_ashr_i32 s15, s14, 31
	v_mad_i64_i32 v[88:89], s[42:43], s37, v88, 0
	v_lshl_add_u64 v[86:87], v[86:87], 2, s[22:23]
	s_lshl_b64 s[40:41], s[14:15], 2
	v_lshl_add_u64 v[88:89], v[88:89], 2, s[22:23]
	v_lshl_add_u64 v[86:87], v[86:87], 0, s[40:41]
	v_mov_b32_e32 v135, v3
	v_lshl_add_u64 v[88:89], v[88:89], 0, s[40:41]
	v_lshl_add_u64 v[86:87], v[86:87], 0, v[134:135]
	v_lshl_add_u64 v[88:89], v[88:89], 0, v[134:135]
	global_load_dwordx4 v[90:93], v[86:87], off nt
	s_nop 0
	global_load_dwordx4 v[86:89], v[88:89], off nt
.LBB0_1480:
	s_or_b64 exec, exec, s[24:25]
	v_mov_b64_e32 v[96:97], v[4:5]
	v_mov_b64_e32 v[100:101], v[4:5]
	v_mov_b64_e32 v[94:95], v[2:3]
	v_mov_b64_e32 v[98:99], v[2:3]
	s_and_saveexec_b64 s[24:25], vcc
	s_cbranch_execz .LBB0_1482
	v_add_u32_e32 v2, s35, v146
	v_mad_i64_i32 v[4:5], s[40:41], s37, v2, 0
	v_add_u32_e32 v2, s35, v147
	s_ashr_i32 s15, s14, 31
	v_mad_i64_i32 v[94:95], s[42:43], s37, v2, 0
	v_lshl_add_u64 v[4:5], v[4:5], 2, s[22:23]
	s_lshl_b64 s[40:41], s[14:15], 2
	v_lshl_add_u64 v[94:95], v[94:95], 2, s[22:23]
	v_lshl_add_u64 v[4:5], v[4:5], 0, s[40:41]
	v_mov_b32_e32 v135, v3
	v_lshl_add_u64 v[94:95], v[94:95], 0, s[40:41]
	v_lshl_add_u64 v[4:5], v[4:5], 0, v[134:135]
	v_lshl_add_u64 v[94:95], v[94:95], 0, v[134:135]
	global_load_dwordx4 v[98:101], v[4:5], off nt
	s_nop 0
	global_load_dwordx4 v[94:97], v[94:95], off nt
; __device__ __forceinline__ void tr_load(const TrItem& t, f32x4 (&v)[16], int lane) {
;     const int c4 = 4 * (lane & 15), kq = lane >> 4; const bool okc = t.n0 + c4 < t.N;
; #pragma unroll
;     for (int i = 0; i < 16; ++i) { v[i] = (f32x4){0.f, 0.f, 0.f, 0.f}; if (okc) v[i] = *(const f32x4*)(t.W + (size_t)(t.k0 + 4 * i + kq) * t.N + t.n0 + c4); }
; }
;     ...
;     for (; it < it1; it += NGW) {
;         const bool more = it + NGW < it1;
;         if (more) { TR_DESCRIBE(it + NGW, tn); tr_load(tn, vn, lane); }
.LBB0_1482:
	s_or_b64 exec, exec, s[24:25]
	v_mov_b32_e32 v4, v3
	v_mov_b32_e32 v5, v3
	v_mov_b32_e32 v2, v3
	v_mov_b64_e32 v[104:105], v[4:5]
	v_mov_b64_e32 v[108:109], v[4:5]
	v_mov_b64_e32 v[102:103], v[2:3]
	v_mov_b64_e32 v[106:107], v[2:3]
	s_and_saveexec_b64 s[24:25], vcc
	s_cbranch_execz .LBB0_1484
	v_add_u32_e32 v102, s35, v148
	v_add_u32_e32 v104, s35, v149
	v_mad_i64_i32 v[102:103], s[40:41], s37, v102, 0
	s_ashr_i32 s15, s14, 31
	v_mad_i64_i32 v[104:105], s[42:43], s37, v104, 0
	v_lshl_add_u64 v[102:103], v[102:103], 2, s[22:23]
	s_lshl_b64 s[40:41], s[14:15], 2
	v_lshl_add_u64 v[104:105], v[104:105], 2, s[22:23]
	v_lshl_add_u64 v[102:103], v[102:103], 0, s[40:41]
	v_mov_b32_e32 v135, v3
	v_lshl_add_u64 v[104:105], v[104:105], 0, s[40:41]
	v_lshl_add_u64 v[102:103], v[102:103], 0, v[134:135]
	v_lshl_add_u64 v[104:105], v[104:105], 0, v[134:135]
	global_load_dwordx4 v[106:109], v[102:103], off nt
	s_nop 0
	global_load_dwordx4 v[102:105], v[104:105], off nt
.LBB0_1484:
	s_or_b64 exec, exec, s[24:25]
	v_mov_b64_e32 v[112:113], v[4:5]
	v_mov_b64_e32 v[116:117], v[4:5]
	v_mov_b64_e32 v[110:111], v[2:3]
	v_mov_b64_e32 v[114:115], v[2:3]
	s_and_saveexec_b64 s[24:25], vcc
	s_cbranch_execz .LBB0_1486
	v_add_u32_e32 v2, s35, v150
	v_mad_i64_i32 v[4:5], s[40:41], s37, v2, 0
	v_add_u32_e32 v2, s35, v151
	s_ashr_i32 s15, s14, 31
	v_mad_i64_i32 v[110:111], s[42:43], s37, v2, 0
	v_lshl_add_u64 v[4:5], v[4:5], 2, s[22:23]
	s_lshl_b64 s[40:41], s[14:15], 2
	v_lshl_add_u64 v[110:111], v[110:111], 2, s[22:23]
	v_lshl_add_u64 v[4:5], v[4:5], 0, s[40:41]
	v_mov_b32_e32 v135, v3
	v_lshl_add_u64 v[110:111], v[110:111], 0, s[40:41]
	v_lshl_add_u64 v[4:5], v[4:5], 0, v[134:135]
	v_lshl_add_u64 v[110:111], v[110:111], 0, v[134:135]
	global_load_dwordx4 v[114:117], v[4:5], off nt
	s_nop 0
	global_load_dwordx4 v[110:113], v[110:111], off nt
.LBB0_1486:
	s_or_b64 exec, exec, s[24:25]
	v_mov_b32_e32 v4, v3
	v_mov_b32_e32 v5, v3
	v_mov_b32_e32 v2, v3
	v_mov_b64_e32 v[120:121], v[4:5]
	v_mov_b64_e32 v[124:125], v[4:5]
	v_mov_b64_e32 v[118:119], v[2:3]
	v_mov_b64_e32 v[122:123], v[2:3]
	s_and_saveexec_b64 s[24:25], vcc
	s_cbranch_execz .LBB0_1488
	v_add_u32_e32 v118, s35, v152
	v_add_u32_e32 v120, s35, v153
	v_mad_i64_i32 v[118:119], s[40:41], s37, v118, 0
	s_ashr_i32 s15, s14, 31
	v_mad_i64_i32 v[120:121], s[42:43], s37, v120, 0
	v_lshl_add_u64 v[118:119], v[118:119], 2, s[22:23]
	s_lshl_b64 s[40:41], s[14:15], 2
	v_lshl_add_u64 v[120:121], v[120:121], 2, s[22:23]
	v_lshl_add_u64 v[118:119], v[118:119], 0, s[40:41]
	v_mov_b32_e32 v135, v3
	v_lshl_add_u64 v[120:121], v[120:121], 0, s[40:41]
	v_lshl_add_u64 v[118:119], v[118:119], 0, v[134:135]
	v_lshl_add_u64 v[120:121], v[120:121], 0, v[134:135]
	global_load_dwordx4 v[122:125], v[118:119], off nt
	s_nop 0
	global_load_dwordx4 v[118:121], v[120:121], off nt
.LBB0_1488:
	s_or_b64 exec, exec, s[24:25]
	v_mov_b64_e32 v[128:129], v[4:5]
	v_mov_b64_e32 v[132:133], v[4:5]
	v_mov_b64_e32 v[126:127], v[2:3]
	v_mov_b64_e32 v[130:131], v[2:3]
	s_and_saveexec_b64 s[24:25], vcc
	s_cbranch_execz .LBB0_1490
	v_add_u32_e32 v2, s35, v154
	v_mad_i64_i32 v[4:5], s[40:41], s37, v2, 0
	v_add_u32_e32 v2, s35, v155
	s_ashr_i32 s15, s14, 31
	v_mad_i64_i32 v[126:127], s[42:43], s37, v2, 0
	v_lshl_add_u64 v[4:5], v[4:5], 2, s[22:23]
	s_lshl_b64 s[40:41], s[14:15], 2
	v_lshl_add_u64 v[126:127], v[126:127], 2, s[22:23]
	v_lshl_add_u64 v[4:5], v[4:5], 0, s[40:41]
	v_mov_b32_e32 v135, v3
	v_lshl_add_u64 v[126:127], v[126:127], 0, s[40:41]
	v_lshl_add_u64 v[4:5], v[4:5], 0, v[134:135]
	v_lshl_add_u64 v[130:131], v[126:127], 0, v[134:135]
	global_load_dwordx4 v[126:129], v[4:5], off nt
	s_nop 0
	global_load_dwordx4 v[130:133], v[130:131], off nt

; __device__ __forceinline__ void tr_load(const TrItem& t, f32x4 (&v)[16], int lane) {
;     const int c4 = 4 * (lane & 15), kq = lane >> 4; const bool okc = t.n0 + c4 < t.N;
; #pragma unroll
;     for (int i = 0; i < 16; ++i) { v[i] = (f32x4){0.f, 0.f, 0.f, 0.f}; if (okc) v[i] = *(const f32x4*)(t.W + (size_t)(t.k0 + 4 * i + kq) * t.N + t.n0 + c4); }
; }
.LBB0_1609:
	v_lshlrev_b32_e32 v2, 2, v72
	v_and_b32_e32 v6, 60, v2
	v_lshrrev_b32_e32 v7, 4, v72
	v_add_u32_e32 v2, s16, v6
	v_mov_b32_e32 v4, v3
	v_mov_b32_e32 v5, v3
	v_cmp_gt_i32_e32 vcc, s35, v2
	v_mov_b32_e32 v2, v3
	v_add_u32_e32 v73, s12, v7
	v_lshlrev_b32_e32 v70, 2, v6
	v_mov_b64_e32 v[12:13], v[4:5]
	v_mov_b64_e32 v[8:9], v[4:5]
	v_mov_b64_e32 v[10:11], v[2:3]
	v_mov_b64_e32 v[6:7], v[2:3]
	s_and_saveexec_b64 s[22:23], vcc
	s_cbranch_execz .LBB0_1611
	v_mad_u64_u32 v[6:7], s[24:25], s35, v73, 0
	v_ashrrev_i32_e32 v9, 31, v73
	v_mov_b32_e32 v8, v7
	v_mad_u64_u32 v[8:9], s[24:25], s35, v9, v[8:9]
	v_mov_b32_e32 v7, v8
	v_add_u32_e32 v8, 4, v73
	v_ashrrev_i32_e32 v11, 31, v8
	v_mad_u64_u32 v[8:9], s[26:27], s35, v8, 0
	v_mov_b32_e32 v10, v9
	v_mad_u64_u32 v[10:11], s[26:27], s35, v11, v[10:11]
	s_ashr_i32 s17, s16, 31
	v_mov_b32_e32 v9, v10
	v_lshl_add_u64 v[6:7], v[6:7], 2, s[20:21]
	s_lshl_b64 s[24:25], s[16:17], 2
	v_lshl_add_u64 v[8:9], v[8:9], 2, s[20:21]
	v_lshl_add_u64 v[6:7], v[6:7], 0, s[24:25]
	v_mov_b32_e32 v71, v3
	v_lshl_add_u64 v[8:9], v[8:9], 0, s[24:25]
	v_lshl_add_u64 v[6:7], v[6:7], 0, v[70:71]
	v_lshl_add_u64 v[10:11], v[8:9], 0, v[70:71]
	global_load_dwordx4 v[6:9], v[6:7], off nt
	s_nop 0
	global_load_dwordx4 v[10:13], v[10:11], off nt
.LBB0_1611:
	s_or_b64 exec, exec, s[22:23]
	v_mov_b64_e32 v[20:21], v[4:5]
	v_mov_b64_e32 v[16:17], v[4:5]
	v_mov_b64_e32 v[18:19], v[2:3]
	v_mov_b64_e32 v[14:15], v[2:3]
	s_and_saveexec_b64 s[22:23], vcc
	s_cbranch_execz .LBB0_1613
	v_add_u32_e32 v2, 8, v73
	v_mad_u64_u32 v[4:5], s[24:25], s35, v2, 0
	v_ashrrev_i32_e32 v14, 31, v2
	v_mov_b32_e32 v2, v5
	v_mad_u64_u32 v[14:15], s[24:25], s35, v14, v[2:3]
	v_add_u32_e32 v2, 12, v73
	v_mov_b32_e32 v5, v14
	v_mad_u64_u32 v[14:15], s[26:27], s35, v2, 0
	v_ashrrev_i32_e32 v16, 31, v2
	v_mov_b32_e32 v2, v15
	v_mad_u64_u32 v[16:17], s[26:27], s35, v16, v[2:3]
	s_ashr_i32 s17, s16, 31
	v_mov_b32_e32 v15, v16
	v_lshl_add_u64 v[4:5], v[4:5], 2, s[20:21]
	s_lshl_b64 s[24:25], s[16:17], 2
	v_lshl_add_u64 v[14:15], v[14:15], 2, s[20:21]
	v_lshl_add_u64 v[4:5], v[4:5], 0, s[24:25]
	v_mov_b32_e32 v71, v3
	v_lshl_add_u64 v[14:15], v[14:15], 0, s[24:25]
	v_lshl_add_u64 v[4:5], v[4:5], 0, v[70:71]
	v_lshl_add_u64 v[18:19], v[14:15], 0, v[70:71]
	global_load_dwordx4 v[14:17], v[4:5], off nt
	s_nop 0
	global_load_dwordx4 v[18:21], v[18:19], off nt
.LBB0_1613:
	s_or_b64 exec, exec, s[22:23]
	v_mov_b32_e32 v4, v3
	v_mov_b32_e32 v5, v3
	v_mov_b32_e32 v2, v3
	v_mov_b64_e32 v[28:29], v[4:5]
	v_mov_b64_e32 v[24:25], v[4:5]
	v_mov_b64_e32 v[26:27], v[2:3]
	v_mov_b64_e32 v[22:23], v[2:3]
	s_and_saveexec_b64 s[22:23], vcc
	s_cbranch_execz .LBB0_1615
	v_add_u32_e32 v22, 16, v73
	v_ashrrev_i32_e32 v25, 31, v22
	v_mad_u64_u32 v[22:23], s[24:25], s35, v22, 0
	v_mov_b32_e32 v24, v23
	v_mad_u64_u32 v[24:25], s[24:25], s35, v25, v[24:25]
	v_mov_b32_e32 v23, v24
	v_add_u32_e32 v24, 20, v73
	v_ashrrev_i32_e32 v27, 31, v24
	v_mad_u64_u32 v[24:25], s[26:27], s35, v24, 0
	v_mov_b32_e32 v26, v25
	v_mad_u64_u32 v[26:27], s[26:27], s35, v27, v[26:27]
	s_ashr_i32 s17, s16, 31
	v_mov_b32_e32 v25, v26
	v_lshl_add_u64 v[22:23], v[22:23], 2, s[20:21]
	s_lshl_b64 s[24:25], s[16:17], 2
	v_lshl_add_u64 v[24:25], v[24:25], 2, s[20:21]
	v_lshl_add_u64 v[22:23], v[22:23], 0, s[24:25]
	v_mov_b32_e32 v71, v3
	v_lshl_add_u64 v[24:25], v[24:25], 0, s[24:25]
	v_lshl_add_u64 v[22:23], v[22:23], 0, v[70:71]
	v_lshl_add_u64 v[26:27], v[24:25], 0, v[70:71]
	global_load_dwordx4 v[22:25], v[22:23], off nt
	s_nop 0
	global_load_dwordx4 v[26:29], v[26:27], off nt
.LBB0_1615:
	s_or_b64 exec, exec, s[22:23]
	v_mov_b64_e32 v[36:37], v[4:5]
	v_mov_b64_e32 v[32:33], v[4:5]
	v_mov_b64_e32 v[34:35], v[2:3]
	v_mov_b64_e32 v[30:31], v[2:3]
	s_and_saveexec_b64 s[22:23], vcc
	s_cbranch_execz .LBB0_1617
	v_add_u32_e32 v2, 24, v73
	v_mad_u64_u32 v[4:5], s[24:25], s35, v2, 0
	v_ashrrev_i32_e32 v30, 31, v2
	v_mov_b32_e32 v2, v5
	v_mad_u64_u32 v[30:31], s[24:25], s35, v30, v[2:3]
	v_add_u32_e32 v2, 28, v73
	v_mov_b32_e32 v5, v30
	v_mad_u64_u32 v[30:31], s[26:27], s35, v2, 0
	v_ashrrev_i32_e32 v32, 31, v2
	v_mov_b32_e32 v2, v31
	v_mad_u64_u32 v[32:33], s[26:27], s35, v32, v[2:3]
	s_ashr_i32 s17, s16, 31
	v_mov_b32_e32 v31, v32
	v_lshl_add_u64 v[4:5], v[4:5], 2, s[20:21]
	s_lshl_b64 s[24:25], s[16:17], 2
	v_lshl_add_u64 v[30:31], v[30:31], 2, s[20:21]
	v_lshl_add_u64 v[4:5], v[4:5], 0, s[24:25]
	v_mov_b32_e32 v71, v3
	v_lshl_add_u64 v[30:31], v[30:31], 0, s[24:25]
	v_lshl_add_u64 v[4:5], v[4:5], 0, v[70:71]
	v_lshl_add_u64 v[34:35], v[30:31], 0, v[70:71]
	global_load_dwordx4 v[30:33], v[4:5], off nt
	s_nop 0
	global_load_dwordx4 v[34:37], v[34:35], off nt
; __device__ __forceinline__ void tr_load(const TrItem& t, f32x4 (&v)[16], int lane) {
;     const int c4 = 4 * (lane & 15), kq = lane >> 4; const bool okc = t.n0 + c4 < t.N;
; #pragma unroll
;     for (int i = 0; i < 16; ++i) { v[i] = (f32x4){0.f, 0.f, 0.f, 0.f}; if (okc) v[i] = *(const f32x4*)(t.W + (size_t)(t.k0 + 4 * i + kq) * t.N + t.n0 + c4); }
; }
.LBB0_1617:
	s_or_b64 exec, exec, s[22:23]
	v_mov_b32_e32 v4, v3
	v_mov_b32_e32 v5, v3
	v_mov_b32_e32 v2, v3
	v_mov_b64_e32 v[44:45], v[4:5]
	v_mov_b64_e32 v[40:41], v[4:5]
	v_mov_b64_e32 v[42:43], v[2:3]
	v_mov_b64_e32 v[38:39], v[2:3]
	s_and_saveexec_b64 s[22:23], vcc
	s_cbranch_execz .LBB0_1619
	v_add_u32_e32 v38, 32, v73
	v_ashrrev_i32_e32 v41, 31, v38
	v_mad_u64_u32 v[38:39], s[24:25], s35, v38, 0
	v_mov_b32_e32 v40, v39
	v_mad_u64_u32 v[40:41], s[24:25], s35, v41, v[40:41]
	v_mov_b32_e32 v39, v40
	v_add_u32_e32 v40, 36, v73
	v_ashrrev_i32_e32 v43, 31, v40
	v_mad_u64_u32 v[40:41], s[26:27], s35, v40, 0
	v_mov_b32_e32 v42, v41
	v_mad_u64_u32 v[42:43], s[26:27], s35, v43, v[42:43]
	s_ashr_i32 s17, s16, 31
	v_mov_b32_e32 v41, v42
	v_lshl_add_u64 v[38:39], v[38:39], 2, s[20:21]
	s_lshl_b64 s[24:25], s[16:17], 2
	v_lshl_add_u64 v[40:41], v[40:41], 2, s[20:21]
	v_lshl_add_u64 v[38:39], v[38:39], 0, s[24:25]
	v_mov_b32_e32 v71, v3
	v_lshl_add_u64 v[40:41], v[40:41], 0, s[24:25]
	v_lshl_add_u64 v[38:39], v[38:39], 0, v[70:71]
	v_lshl_add_u64 v[42:43], v[40:41], 0, v[70:71]
	global_load_dwordx4 v[38:41], v[38:39], off nt
	s_nop 0
	global_load_dwordx4 v[42:45], v[42:43], off nt
.LBB0_1619:
	s_or_b64 exec, exec, s[22:23]
	v_mov_b64_e32 v[52:53], v[4:5]
	v_mov_b64_e32 v[48:49], v[4:5]
	v_mov_b64_e32 v[50:51], v[2:3]
	v_mov_b64_e32 v[46:47], v[2:3]
	s_and_saveexec_b64 s[22:23], vcc
	s_cbranch_execz .LBB0_1621
	v_add_u32_e32 v2, 40, v73
	v_mad_u64_u32 v[4:5], s[24:25], s35, v2, 0
	v_ashrrev_i32_e32 v46, 31, v2
	v_mov_b32_e32 v2, v5
	v_mad_u64_u32 v[46:47], s[24:25], s35, v46, v[2:3]
	v_add_u32_e32 v2, 44, v73
	v_mov_b32_e32 v5, v46
	v_mad_u64_u32 v[46:47], s[26:27], s35, v2, 0
	v_ashrrev_i32_e32 v48, 31, v2
	v_mov_b32_e32 v2, v47
	v_mad_u64_u32 v[48:49], s[26:27], s35, v48, v[2:3]
	s_ashr_i32 s17, s16, 31
	v_mov_b32_e32 v47, v48
	v_lshl_add_u64 v[4:5], v[4:5], 2, s[20:21]
	s_lshl_b64 s[24:25], s[16:17], 2
	v_lshl_add_u64 v[46:47], v[46:47], 2, s[20:21]
	v_lshl_add_u64 v[4:5], v[4:5], 0, s[24:25]
	v_mov_b32_e32 v71, v3
	v_lshl_add_u64 v[46:47], v[46:47], 0, s[24:25]
	v_lshl_add_u64 v[4:5], v[4:5], 0, v[70:71]
	v_lshl_add_u64 v[50:51], v[46:47], 0, v[70:71]
	global_load_dwordx4 v[46:49], v[4:5], off nt
	s_nop 0
	global_load_dwordx4 v[50:53], v[50:51], off nt
.LBB0_1621:
	s_or_b64 exec, exec, s[22:23]
	v_mov_b32_e32 v4, v3
	v_mov_b32_e32 v5, v3
	v_mov_b32_e32 v2, v3
	v_mov_b64_e32 v[60:61], v[4:5]
	v_mov_b64_e32 v[56:57], v[4:5]
	v_mov_b64_e32 v[58:59], v[2:3]
	v_mov_b64_e32 v[54:55], v[2:3]
	s_and_saveexec_b64 s[22:23], vcc
	s_cbranch_execz .LBB0_1623
	v_add_u32_e32 v54, 48, v73
	v_ashrrev_i32_e32 v57, 31, v54
	v_mad_u64_u32 v[54:55], s[24:25], s35, v54, 0
	v_mov_b32_e32 v56, v55
	v_mad_u64_u32 v[56:57], s[24:25], s35, v57, v[56:57]
	v_mov_b32_e32 v55, v56
	v_add_u32_e32 v56, 52, v73
	v_ashrrev_i32_e32 v59, 31, v56
	v_mad_u64_u32 v[56:57], s[26:27], s35, v56, 0
	v_mov_b32_e32 v58, v57
	v_mad_u64_u32 v[58:59], s[26:27], s35, v59, v[58:59]
	s_ashr_i32 s17, s16, 31
	v_mov_b32_e32 v57, v58
	v_lshl_add_u64 v[54:55], v[54:55], 2, s[20:21]
	s_lshl_b64 s[24:25], s[16:17], 2
	v_lshl_add_u64 v[56:57], v[56:57], 2, s[20:21]
	v_lshl_add_u64 v[54:55], v[54:55], 0, s[24:25]
	v_mov_b32_e32 v71, v3
	v_lshl_add_u64 v[56:57], v[56:57], 0, s[24:25]
	v_lshl_add_u64 v[54:55], v[54:55], 0, v[70:71]
	v_lshl_add_u64 v[58:59], v[56:57], 0, v[70:71]
	global_load_dwordx4 v[54:57], v[54:55], off nt
	s_nop 0
	global_load_dwordx4 v[58:61], v[58:59], off nt
.LBB0_1623:
	s_or_b64 exec, exec, s[22:23]
	v_mov_b64_e32 v[64:65], v[4:5]
	v_mov_b64_e32 v[68:69], v[4:5]
	v_mov_b64_e32 v[62:63], v[2:3]
	v_mov_b64_e32 v[66:67], v[2:3]
	s_and_saveexec_b64 s[22:23], vcc
	s_cbranch_execz .LBB0_1625
	v_add_u32_e32 v2, 56, v73
	v_mad_u64_u32 v[4:5], s[24:25], s35, v2, 0
	v_ashrrev_i32_e32 v62, 31, v2
	v_mov_b32_e32 v2, v5
	v_mad_u64_u32 v[62:63], s[24:25], s35, v62, v[2:3]
	v_add_u32_e32 v2, 60, v73
	v_mov_b32_e32 v5, v62
	v_mad_u64_u32 v[62:63], s[26:27], s35, v2, 0
	v_ashrrev_i32_e32 v64, 31, v2
	v_mov_b32_e32 v2, v63
	v_mad_u64_u32 v[64:65], s[26:27], s35, v64, v[2:3]
	s_ashr_i32 s17, s16, 31
	v_mov_b32_e32 v63, v64
	v_lshl_add_u64 v[4:5], v[4:5], 2, s[20:21]
	s_lshl_b64 s[24:25], s[16:17], 2
	v_lshl_add_u64 v[62:63], v[62:63], 2, s[20:21]
	v_lshl_add_u64 v[4:5], v[4:5], 0, s[24:25]
	v_mov_b32_e32 v71, v3
	v_lshl_add_u64 v[62:63], v[62:63], 0, s[24:25]
	v_lshl_add_u64 v[4:5], v[4:5], 0, v[70:71]
	v_lshl_add_u64 v[66:67], v[62:63], 0, v[70:71]
	global_load_dwordx4 v[62:65], v[4:5], off nt
	s_nop 0
	global_load_dwordx4 v[66:69], v[66:67], off nt

; __device__ __forceinline__ void tr_load(const TrItem& t, f32x4 (&v)[16], int lane) {
;     const int c4 = 4 * (lane & 15), kq = lane >> 4; const bool okc = t.n0 + c4 < t.N;
; #pragma unroll
;     for (int i = 0; i < 16; ++i) { v[i] = (f32x4){0.f, 0.f, 0.f, 0.f}; if (okc) v[i] = *(const f32x4*)(t.W + (size_t)(t.k0 + 4 * i + kq) * t.N + t.n0 + c4); }
;     ...
;     for (; it < it1; it += NGW) {
;         const bool more = it + NGW < it1;
;         if (more) { TR_DESCRIBE(it + NGW, tn); tr_load(tn, vn, lane); }
.LBB0_1637:
	v_or_b32_e32 v2, s18, v138
	v_mov_b32_e32 v4, v3
	v_mov_b32_e32 v5, v3
	v_cmp_gt_i32_e32 vcc, s41, v2
	v_mov_b32_e32 v2, v3
	v_mov_b64_e32 v[72:73], v[4:5]
	v_mov_b64_e32 v[76:77], v[4:5]
	v_lshlrev_b32_e32 v134, 2, v138
	v_mov_b64_e32 v[70:71], v[2:3]
	v_mov_b64_e32 v[74:75], v[2:3]
	s_and_saveexec_b64 s[28:29], vcc
	s_cbranch_execz .LBB0_1639
	v_add_u32_e32 v70, s39, v139
	v_ashrrev_i32_e32 v73, 31, v70
	v_mad_u64_u32 v[70:71], s[44:45], s41, v70, 0
	v_mov_b32_e32 v72, v71
	v_mad_u64_u32 v[72:73], s[44:45], s41, v73, v[72:73]
	v_mov_b32_e32 v71, v72
	v_add_u32_e32 v72, s39, v141
	v_ashrrev_i32_e32 v75, 31, v72
	v_mad_u64_u32 v[72:73], s[46:47], s41, v72, 0
	v_mov_b32_e32 v74, v73
	v_mad_u64_u32 v[74:75], s[46:47], s41, v75, v[74:75]
	s_ashr_i32 s19, s18, 31
	v_mov_b32_e32 v73, v74
	v_lshl_add_u64 v[70:71], v[70:71], 2, s[26:27]
	s_lshl_b64 s[44:45], s[18:19], 2
	v_lshl_add_u64 v[72:73], v[72:73], 2, s[26:27]
	v_lshl_add_u64 v[70:71], v[70:71], 0, s[44:45]
	v_mov_b32_e32 v135, v3
	v_lshl_add_u64 v[72:73], v[72:73], 0, s[44:45]
	v_lshl_add_u64 v[70:71], v[70:71], 0, v[134:135]
	v_lshl_add_u64 v[72:73], v[72:73], 0, v[134:135]
	global_load_dwordx4 v[74:77], v[70:71], off nt
	s_nop 0
	global_load_dwordx4 v[70:73], v[72:73], off nt
.LBB0_1639:
	s_or_b64 exec, exec, s[28:29]
	v_mov_b64_e32 v[80:81], v[4:5]
	v_mov_b64_e32 v[84:85], v[4:5]
	v_mov_b64_e32 v[78:79], v[2:3]
	v_mov_b64_e32 v[82:83], v[2:3]
	s_and_saveexec_b64 s[28:29], vcc
	s_cbranch_execz .LBB0_1641
	v_add_u32_e32 v2, s39, v142
	v_mad_u64_u32 v[4:5], s[44:45], s41, v2, 0
	v_ashrrev_i32_e32 v78, 31, v2
	v_mov_b32_e32 v2, v5
	v_mad_u64_u32 v[78:79], s[44:45], s41, v78, v[2:3]
	v_add_u32_e32 v2, s39, v143
	v_mov_b32_e32 v5, v78
	v_mad_u64_u32 v[78:79], s[46:47], s41, v2, 0
	v_ashrrev_i32_e32 v80, 31, v2
	v_mov_b32_e32 v2, v79
	v_mad_u64_u32 v[80:81], s[46:47], s41, v80, v[2:3]
	s_ashr_i32 s19, s18, 31
	v_mov_b32_e32 v79, v80
	v_lshl_add_u64 v[4:5], v[4:5], 2, s[26:27]
	s_lshl_b64 s[44:45], s[18:19], 2
	v_lshl_add_u64 v[78:79], v[78:79], 2, s[26:27]
	v_lshl_add_u64 v[4:5], v[4:5], 0, s[44:45]
	v_mov_b32_e32 v135, v3
	v_lshl_add_u64 v[78:79], v[78:79], 0, s[44:45]
	v_lshl_add_u64 v[4:5], v[4:5], 0, v[134:135]
	v_lshl_add_u64 v[78:79], v[78:79], 0, v[134:135]
	global_load_dwordx4 v[82:85], v[4:5], off nt
	s_nop 0
	global_load_dwordx4 v[78:81], v[78:79], off nt
.LBB0_1641:
	s_or_b64 exec, exec, s[28:29]
	v_mov_b32_e32 v4, v3
	v_mov_b32_e32 v5, v3
	v_mov_b32_e32 v2, v3
	v_mov_b64_e32 v[88:89], v[4:5]
	v_mov_b64_e32 v[92:93], v[4:5]
	v_mov_b64_e32 v[86:87], v[2:3]
	v_mov_b64_e32 v[90:91], v[2:3]
	s_and_saveexec_b64 s[28:29], vcc
	s_cbranch_execz .LBB0_1643
	v_add_u32_e32 v86, s39, v144
	v_ashrrev_i32_e32 v89, 31, v86
	v_mad_u64_u32 v[86:87], s[44:45], s41, v86, 0
	v_mov_b32_e32 v88, v87
	v_mad_u64_u32 v[88:89], s[44:45], s41, v89, v[88:89]
	v_mov_b32_e32 v87, v88
	v_add_u32_e32 v88, s39, v145
	v_ashrrev_i32_e32 v91, 31, v88
	v_mad_u64_u32 v[88:89], s[46:47], s41, v88, 0
	v_mov_b32_e32 v90, v89
	v_mad_u64_u32 v[90:91], s[46:47], s41, v91, v[90:91]
	s_ashr_i32 s19, s18, 31
	v_mov_b32_e32 v89, v90
	v_lshl_add_u64 v[86:87], v[86:87], 2, s[26:27]
	s_lshl_b64 s[44:45], s[18:19], 2
	v_lshl_add_u64 v[88:89], v[88:89], 2, s[26:27]
	v_lshl_add_u64 v[86:87], v[86:87], 0, s[44:45]
	v_mov_b32_e32 v135, v3
	v_lshl_add_u64 v[88:89], v[88:89], 0, s[44:45]
	v_lshl_add_u64 v[86:87], v[86:87], 0, v[134:135]
	v_lshl_add_u64 v[88:89], v[88:89], 0, v[134:135]
	global_load_dwordx4 v[90:93], v[86:87], off nt
	s_nop 0
	global_load_dwordx4 v[86:89], v[88:89], off nt
.LBB0_1643:
	s_or_b64 exec, exec, s[28:29]
	v_mov_b64_e32 v[96:97], v[4:5]
	v_mov_b64_e32 v[100:101], v[4:5]
	v_mov_b64_e32 v[94:95], v[2:3]
	v_mov_b64_e32 v[98:99], v[2:3]
	s_and_saveexec_b64 s[28:29], vcc
	s_cbranch_execz .LBB0_1645
	v_add_u32_e32 v2, s39, v146
	v_mad_u64_u32 v[4:5], s[44:45], s41, v2, 0
	v_ashrrev_i32_e32 v94, 31, v2
	v_mov_b32_e32 v2, v5
	v_mad_u64_u32 v[94:95], s[44:45], s41, v94, v[2:3]
	v_add_u32_e32 v2, s39, v147
	v_mov_b32_e32 v5, v94
	v_mad_u64_u32 v[94:95], s[46:47], s41, v2, 0
	v_ashrrev_i32_e32 v96, 31, v2
	v_mov_b32_e32 v2, v95
	v_mad_u64_u32 v[96:97], s[46:47], s41, v96, v[2:3]
	s_ashr_i32 s19, s18, 31
	v_mov_b32_e32 v95, v96
	v_lshl_add_u64 v[4:5], v[4:5], 2, s[26:27]
	s_lshl_b64 s[44:45], s[18:19], 2
	v_lshl_add_u64 v[94:95], v[94:95], 2, s[26:27]
	v_lshl_add_u64 v[4:5], v[4:5], 0, s[44:45]
	v_mov_b32_e32 v135, v3
	v_lshl_add_u64 v[94:95], v[94:95], 0, s[44:45]
	v_lshl_add_u64 v[4:5], v[4:5], 0, v[134:135]
	v_lshl_add_u64 v[94:95], v[94:95], 0, v[134:135]
	global_load_dwordx4 v[98:101], v[4:5], off nt
	s_nop 0
	global_load_dwordx4 v[94:97], v[94:95], off nt
; __device__ __forceinline__ void tr_load(const TrItem& t, f32x4 (&v)[16], int lane) {
;     const int c4 = 4 * (lane & 15), kq = lane >> 4; const bool okc = t.n0 + c4 < t.N;
; #pragma unroll
;     for (int i = 0; i < 16; ++i) { v[i] = (f32x4){0.f, 0.f, 0.f, 0.f}; if (okc) v[i] = *(const f32x4*)(t.W + (size_t)(t.k0 + 4 * i + kq) * t.N + t.n0 + c4); }
;     ...
;     for (; it < it1; it += NGW) {
;         const bool more = it + NGW < it1;
;         if (more) { TR_DESCRIBE(it + NGW, tn); tr_load(tn, vn, lane); }
.LBB0_1645:
	s_or_b64 exec, exec, s[28:29]
	v_mov_b32_e32 v4, v3
	v_mov_b32_e32 v5, v3
	v_mov_b32_e32 v2, v3
	v_mov_b64_e32 v[104:105], v[4:5]
	v_mov_b64_e32 v[108:109], v[4:5]
	v_mov_b64_e32 v[102:103], v[2:3]
	v_mov_b64_e32 v[106:107], v[2:3]
	s_and_saveexec_b64 s[28:29], vcc
	s_cbranch_execz .LBB0_1647
	v_add_u32_e32 v102, s39, v148
	v_ashrrev_i32_e32 v105, 31, v102
	v_mad_u64_u32 v[102:103], s[44:45], s41, v102, 0
	v_mov_b32_e32 v104, v103
	v_mad_u64_u32 v[104:105], s[44:45], s41, v105, v[104:105]
	v_mov_b32_e32 v103, v104
	v_add_u32_e32 v104, s39, v149
	v_ashrrev_i32_e32 v107, 31, v104
	v_mad_u64_u32 v[104:105], s[46:47], s41, v104, 0
	v_mov_b32_e32 v106, v105
	v_mad_u64_u32 v[106:107], s[46:47], s41, v107, v[106:107]
	s_ashr_i32 s19, s18, 31
	v_mov_b32_e32 v105, v106
	v_lshl_add_u64 v[102:103], v[102:103], 2, s[26:27]
	s_lshl_b64 s[44:45], s[18:19], 2
	v_lshl_add_u64 v[104:105], v[104:105], 2, s[26:27]
	v_lshl_add_u64 v[102:103], v[102:103], 0, s[44:45]
	v_mov_b32_e32 v135, v3
	v_lshl_add_u64 v[104:105], v[104:105], 0, s[44:45]
	v_lshl_add_u64 v[102:103], v[102:103], 0, v[134:135]
	v_lshl_add_u64 v[104:105], v[104:105], 0, v[134:135]
	global_load_dwordx4 v[106:109], v[102:103], off nt
	s_nop 0
	global_load_dwordx4 v[102:105], v[104:105], off nt
.LBB0_1647:
	s_or_b64 exec, exec, s[28:29]
	v_mov_b64_e32 v[112:113], v[4:5]
	v_mov_b64_e32 v[116:117], v[4:5]
	v_mov_b64_e32 v[110:111], v[2:3]
	v_mov_b64_e32 v[114:115], v[2:3]
	s_and_saveexec_b64 s[28:29], vcc
	s_cbranch_execz .LBB0_1649
	v_add_u32_e32 v2, s39, v150
	v_mad_u64_u32 v[4:5], s[44:45], s41, v2, 0
	v_ashrrev_i32_e32 v110, 31, v2
	v_mov_b32_e32 v2, v5
	v_mad_u64_u32 v[110:111], s[44:45], s41, v110, v[2:3]
	v_add_u32_e32 v2, s39, v151
	v_mov_b32_e32 v5, v110
	v_mad_u64_u32 v[110:111], s[46:47], s41, v2, 0
	v_ashrrev_i32_e32 v112, 31, v2
	v_mov_b32_e32 v2, v111
	v_mad_u64_u32 v[112:113], s[46:47], s41, v112, v[2:3]
	s_ashr_i32 s19, s18, 31
	v_mov_b32_e32 v111, v112
	v_lshl_add_u64 v[4:5], v[4:5], 2, s[26:27]
	s_lshl_b64 s[44:45], s[18:19], 2
	v_lshl_add_u64 v[110:111], v[110:111], 2, s[26:27]
	v_lshl_add_u64 v[4:5], v[4:5], 0, s[44:45]
	v_mov_b32_e32 v135, v3
	v_lshl_add_u64 v[110:111], v[110:111], 0, s[44:45]
	v_lshl_add_u64 v[4:5], v[4:5], 0, v[134:135]
	v_lshl_add_u64 v[110:111], v[110:111], 0, v[134:135]
	global_load_dwordx4 v[114:117], v[4:5], off nt
	s_nop 0
	global_load_dwordx4 v[110:113], v[110:111], off nt
.LBB0_1649:
	s_or_b64 exec, exec, s[28:29]
	v_mov_b32_e32 v4, v3
	v_mov_b32_e32 v5, v3
	v_mov_b32_e32 v2, v3
	v_mov_b64_e32 v[120:121], v[4:5]
	v_mov_b64_e32 v[124:125], v[4:5]
	v_mov_b64_e32 v[118:119], v[2:3]
	v_mov_b64_e32 v[122:123], v[2:3]
	s_and_saveexec_b64 s[28:29], vcc
	s_cbranch_execz .LBB0_1651
	v_add_u32_e32 v118, s39, v152
	v_ashrrev_i32_e32 v121, 31, v118
	v_mad_u64_u32 v[118:119], s[44:45], s41, v118, 0
	v_mov_b32_e32 v120, v119
	v_mad_u64_u32 v[120:121], s[44:45], s41, v121, v[120:121]
	v_mov_b32_e32 v119, v120
	v_add_u32_e32 v120, s39, v153
	v_ashrrev_i32_e32 v123, 31, v120
	v_mad_u64_u32 v[120:121], s[46:47], s41, v120, 0
	v_mov_b32_e32 v122, v121
	v_mad_u64_u32 v[122:123], s[46:47], s41, v123, v[122:123]
	s_ashr_i32 s19, s18, 31
	v_mov_b32_e32 v121, v122
	v_lshl_add_u64 v[118:119], v[118:119], 2, s[26:27]
	s_lshl_b64 s[44:45], s[18:19], 2
	v_lshl_add_u64 v[120:121], v[120:121], 2, s[26:27]
	v_lshl_add_u64 v[118:119], v[118:119], 0, s[44:45]
	v_mov_b32_e32 v135, v3
	v_lshl_add_u64 v[120:121], v[120:121], 0, s[44:45]
	v_lshl_add_u64 v[118:119], v[118:119], 0, v[134:135]
	v_lshl_add_u64 v[120:121], v[120:121], 0, v[134:135]
	global_load_dwordx4 v[122:125], v[118:119], off nt
	s_nop 0
	global_load_dwordx4 v[118:121], v[120:121], off nt
.LBB0_1651:
	s_or_b64 exec, exec, s[28:29]
	v_mov_b64_e32 v[128:129], v[4:5]
	v_mov_b64_e32 v[132:133], v[4:5]
	v_mov_b64_e32 v[126:127], v[2:3]
	v_mov_b64_e32 v[130:131], v[2:3]
	s_and_saveexec_b64 s[28:29], vcc
	s_cbranch_execz .LBB0_1653
	v_add_u32_e32 v2, s39, v154
	v_mad_u64_u32 v[4:5], s[44:45], s41, v2, 0
	v_ashrrev_i32_e32 v126, 31, v2
	v_mov_b32_e32 v2, v5
	v_mad_u64_u32 v[126:127], s[44:45], s41, v126, v[2:3]
	v_add_u32_e32 v2, s39, v155
	v_mov_b32_e32 v5, v126
	v_mad_u64_u32 v[126:127], s[46:47], s41, v2, 0
	v_ashrrev_i32_e32 v128, 31, v2
	v_mov_b32_e32 v2, v127
	v_mad_u64_u32 v[128:129], s[46:47], s41, v128, v[2:3]
	s_ashr_i32 s19, s18, 31
	v_mov_b32_e32 v127, v128
	v_lshl_add_u64 v[4:5], v[4:5], 2, s[26:27]
	s_lshl_b64 s[44:45], s[18:19], 2
	v_lshl_add_u64 v[126:127], v[126:127], 2, s[26:27]
	v_lshl_add_u64 v[4:5], v[4:5], 0, s[44:45]
	v_mov_b32_e32 v135, v3
	v_lshl_add_u64 v[126:127], v[126:127], 0, s[44:45]
	v_lshl_add_u64 v[4:5], v[4:5], 0, v[134:135]
	v_lshl_add_u64 v[130:131], v[126:127], 0, v[134:135]
	global_load_dwordx4 v[126:129], v[4:5], off nt
	s_nop 0
	global_load_dwordx4 v[130:133], v[130:131], off nt
